# diff-attn: fuse both V halves into one QK/softmax pass (2 units per q-block instead of 4), o2/o3 accumulators in freed VGPRs
# speedup vs baseline: 1.0747x; 1.0747x over previous
; __global__ void __launch_bounds__(512, 2) fwd_kernel(Args A) {
;     ...
;             for (int rep_ = 0; rep_ < REP_ATT; ++rep_) {
;                 const int bhd = (Ga == 256) ? (vcu >> 4) : 0, jq = vcu & 15; const int b = bhd >> 2, hh = bhd & 3;
;                 if (Ga == 256) {
;                     for (int sub = 0; sub < 4; ++sub)
;                         for (int grp = 0; grp < 2; ++grp) {
;                             int tidA = tid0; asm volatile("" : "+v"(tidA));
;                             const int c = sub >> 1, half = (sub ^ (sub >> 1)) & 1, vh = hh * 4 + c * 2 + half, qb = grp ? jq : 31 - jq;
;                             attn_body::attn_unit<ATT_THRL>(b, (2 * hh + c) * 64, 512 + (2 * hh + c) * 64, 1024 + hh * 128 + half * 64, vh * 64, qb,
;                                                     (const attn_body::bf16*)HB, (const attn_body::bf16*)HB, (const attn_body::bf16*)HB, (attn_body::bf16*)AUX, (char*)lds_raw, tidA);
.LBB0_204:
	s_andn2_b64 vcc, exec, s[2:3]
	s_cbranch_vccnz .LBB0_400
	s_and_b64 s[2:3], s[6:7], exec
	v_readlane_b32 s0, v255, 15
	s_cselect_b32 s3, s0, 0
	s_ashr_i32 s2, s3, 2
	s_and_b32 s26, s3, 3
	s_ashr_i32 s3, s2, 31
	s_lshl_b32 s27, s26, 2
	s_lshl_b32 s24, s26, 7
	s_lshl_b64 s[6:7], s[2:3], 13
	s_mul_hi_i32 s3, s2, 0x3800000
	s_mul_i32 s2, s2, 0x3800000
	s_add_u32 s28, s84, s2
	s_mov_b32 s25, 0
	s_addc_u32 s29, s85, s3
	v_readlane_b32 s1, v255, 17
	v_readlane_b32 s33, v253, 25
	v_readlane_b32 s74, v253, 57
	v_readlane_b32 s75, v253, 58
	v_readlane_b32 s76, v255, 16
	v_mbcnt_lo_u32_b32 v0, -1, 0
	v_mbcnt_hi_u32_b32 v0, -1, v0
	v_add_u32_e32 v0, s33, v0
	v_lshlrev_b32_e32 v0, 2, v0
	v_add_u32_e32 v0, 0x1a800, v0
	ds_write_b32 v0, v226
	ds_write_b32 v0, v244 offset:2048
	ds_write_b32 v0, v245 offset:4096
	ds_write_b32 v0, v247 offset:6144
	ds_write_b32 v0, v250 offset:8192
	ds_write_b32 v0, v253 offset:10240
	ds_write_b32 v0, v254 offset:12288
	ds_write_b32 v0, v255 offset:14336
	s_waitcnt lgkmcnt(0)
	s_branch .LBB0_236

; __device__ __forceinline__ int crow(int r,int hi){return (r&3)+8*(r>>2)+4*hi;}
; __device__ __forceinline__ int crow(int reg, int h) { return (reg & 3) + 8 * (reg >> 2) + 4 * h; }
; template<int THRL> __device__ __forceinline__ void attn_unit(int b,int colq,int colk,int colv,int colo,int qb,const bf16*Q,const bf16*__restrict__ K,const bf16*__restrict__ V,bf16*O,char*shm,const int tid_in){
;     ...
;   {auto rr=__builtin_amdgcn_permlane32_swap(__float_as_uint(l_reg),__float_as_uint(l_reg),false,false);l_reg=__uint_as_float(rr[0])+__uint_as_float(rr[1]);}
;   if(hi==0)wsf[32+r32]=l_reg;asm volatile("s_waitcnt lgkmcnt(0)":::"memory");
;   float rli[16];
;   #pragma unroll
;   for(int r=0;r<16;++r)rli[r]=__builtin_amdgcn_rcpf(wsf[32+crow(r,hi)]);
;   bf16*Ow=O+(rowbase+q0+wid*QBLK)*DMO+colo;
;   { bf16*stg=(bf16*)(shm+LDS_OST)+wid*2048;
;     #pragma unroll
;     for(int r=0;r<16;++r){const int orow=crow(r,hi);
;       #pragma unroll
;       for(int d0=0;d0<2;++d0)stg[orow*64+d0*32+r32]=__float2bfloat16(o[d0][r]*rli[r]);}
;     asm volatile("s_waitcnt lgkmcnt(0)":::"memory");
;     #pragma unroll
;     for(int i=0;i<4;++i){const int row=i*8+(lane>>3),ch=lane&7; const u32x4 v=*(const u32x4*)(stg+row*64+ch*8); ATTN_STORE16(Ow+(long)row*DMO+ch*8,v);} }
; __global__ void __launch_bounds__(512, 2) fwd_kernel(Args A) {
;     ...
;                     for (int sub = 0; sub < 4; ++sub)
;                         for (int grp = 0; grp < 2; ++grp) {
;                             int tidA = tid0; asm volatile("" : "+v"(tidA));
;                             const int c = sub >> 1, half = (sub ^ (sub >> 1)) & 1, vh = hh * 4 + c * 2 + half, qb = grp ? jq : 31 - jq;
;                             attn_body::attn_unit<ATT_THRL>(b, (2 * hh + c) * 64, 512 + (2 * hh + c) * 64, 1024 + hh * 128 + half * 64, vh * 64, qb,
;                                                     (const attn_body::bf16*)HB, (const attn_body::bf16*)HB, (const attn_body::bf16*)HB, (attn_body::bf16*)AUX, (char*)lds_raw, tidA);
.LBB0_235:
	s_add_i32 s25, s25, 3
	s_cmp_eq_u32 s25, 6
	s_cbranch_scc1 .LBB0_397
.LBB0_236:
	s_lshr_b32 s2, s25, 1
	s_and_b32 s3, s25, 1
	s_and_b32 s4, s25, 2
	s_xor_b32 s3, s3, s2
	s_or_b32 s4, s4, s27
	s_lshl_b32 s2, s2, 6
	s_add_i32 s4, s4, s3
	s_add_i32 s2, s2, s24
	s_lshl_b32 s3, s3, 6
	s_add_i32 s3, s3, s24
	s_lshl_b32 s2, s2, 1
	s_add_u32 s30, s84, s2
	s_addc_u32 s31, s85, 0
	s_add_u32 s8, s28, s2
	s_addc_u32 s9, s29, 0
	s_lshl_b32 s2, s3, 1
	s_add_u32 s10, s28, s2
	s_addc_u32 s11, s29, 0
	s_lshl_b32 s2, s4, 7
	s_mov_b32 s0, s74
	s_add_u32 s34, s0, s2
	s_mov_b32 s0, s75
	s_addc_u32 s35, s0, 0
	s_mov_b64 s[4:5], -1
	s_mov_b32 s0, s76
	s_branch .LBB0_238
.LBB0_237:
	s_or_b64 exec, exec, s[2:3]
	s_waitcnt lgkmcnt(0)
	ds_read_b128 v[4:7], v2 offset:49280
	ds_read_b128 v[8:11], v2 offset:49312
	s_lshl_b32 s4, s36, 12
	s_add_i32 s4, s4, 0
	v_lshlrev_b32_e32 v50, 9, v243
	s_waitcnt lgkmcnt(1)
	v_rcp_f32_e32 v0, v4
	v_rcp_f32_e32 v3, v5
	v_rcp_f32_e32 v12, v6
	v_rcp_f32_e32 v13, v7
	s_waitcnt lgkmcnt(0)
	v_rcp_f32_e32 v14, v8
	ds_read_b128 v[4:7], v2 offset:49344
	v_rcp_f32_e32 v15, v9
	v_rcp_f32_e32 v48, v10
	v_rcp_f32_e32 v49, v11
	ds_read_b128 v[8:11], v2 offset:49376
	s_waitcnt lgkmcnt(1)
	v_rcp_f32_e32 v2, v4
	v_rcp_f32_e32 v4, v5
	v_rcp_f32_e32 v5, v6
	v_rcp_f32_e32 v6, v7
	s_waitcnt lgkmcnt(0)
	v_rcp_f32_e32 v7, v8
	v_rcp_f32_e32 v8, v9
	v_rcp_f32_e32 v9, v10
	v_rcp_f32_e32 v10, v11
	v_lshlrev_b32_e32 v11, 1, v242
	v_mul_f32_e32 v32, v32, v0
	v_mul_f32_e32 v0, v16, v0
	v_add3_u32 v11, s4, v11, v50
	v_cvt_pk_bf16_f32 v0, v0, s0
	ds_write_b16 v11, v0 offset:51264
	v_mul_f32_e32 v0, v33, v3
	v_cvt_pk_bf16_f32 v0, v0, s0
	ds_write_b16 v11, v0 offset:51328
	v_mul_f32_e32 v0, v17, v3
	v_cvt_pk_bf16_f32 v0, v0, s0
	ds_write_b16 v11, v0 offset:51392
	v_mul_f32_e32 v0, v34, v12
	v_cvt_pk_bf16_f32 v0, v0, s0
	ds_write_b16 v11, v0 offset:51456
	v_mul_f32_e32 v0, v18, v12
	v_cvt_pk_bf16_f32 v0, v0, s0
	ds_write_b16 v11, v0 offset:51520
	v_mul_f32_e32 v0, v35, v13
	v_cvt_pk_bf16_f32 v0, v0, s0
	ds_write_b16 v11, v0 offset:51584
	v_mul_f32_e32 v0, v19, v13
	v_cvt_pk_bf16_f32 v0, v0, s0
	ds_write_b16 v11, v0 offset:51648
	v_mul_f32_e32 v0, v36, v14
	v_cvt_pk_bf16_f32 v0, v0, s0
	ds_write_b16 v11, v0 offset:52224
	v_mul_f32_e32 v0, v20, v14
	v_cvt_pk_bf16_f32 v0, v0, s0
	ds_write_b16 v11, v0 offset:52288
	v_mul_f32_e32 v0, v37, v15
	v_cvt_pk_bf16_f32 v0, v0, s0
	ds_write_b16 v11, v0 offset:52352
	v_mul_f32_e32 v0, v21, v15
	v_cvt_pk_bf16_f32 v0, v0, s0
	ds_write_b16 v11, v0 offset:52416
	v_mul_f32_e32 v0, v38, v48
	v_cvt_pk_bf16_f32 v0, v0, s0
	ds_write_b16 v11, v0 offset:52480
	v_mul_f32_e32 v0, v22, v48
	v_cvt_pk_bf16_f32 v0, v0, s0
	ds_write_b16 v11, v0 offset:52544
	v_mul_f32_e32 v0, v39, v49
	v_cvt_pk_bf16_f32 v0, v0, s0
	ds_write_b16 v11, v0 offset:52608
	v_mul_f32_e32 v0, v23, v49
	v_cvt_pk_bf16_f32 v0, v0, s0
	ds_write_b16 v11, v0 offset:52672
	v_mul_f32_e32 v0, v40, v2
	v_cvt_pk_bf16_f32 v0, v0, s0
	ds_write_b16 v11, v0 offset:53248
	v_mul_f32_e32 v0, v24, v2
	v_cvt_pk_bf16_f32 v0, v0, s0
	ds_write_b16 v11, v0 offset:53312
	v_mul_f32_e32 v0, v41, v4
	v_cvt_pk_bf16_f32 v0, v0, s0
	ds_write_b16 v11, v0 offset:53376
	v_mul_f32_e32 v0, v25, v4
	v_cvt_pk_bf16_f32 v0, v0, s0
	ds_write_b16 v11, v0 offset:53440
	v_mul_f32_e32 v0, v42, v5
	v_cvt_pk_bf16_f32 v0, v0, s0
	ds_write_b16 v11, v0 offset:53504
	v_mul_f32_e32 v0, v26, v5
	v_cvt_pk_bf16_f32 v0, v0, s0
	ds_write_b16 v11, v0 offset:53568
	v_mul_f32_e32 v0, v43, v6
	v_cvt_pk_bf16_f32 v0, v0, s0
	ds_write_b16 v11, v0 offset:53632
	v_mul_f32_e32 v0, v27, v6
	v_cvt_pk_bf16_f32 v0, v0, s0
	ds_write_b16 v11, v0 offset:53696
	v_mul_f32_e32 v0, v44, v7
	v_cvt_pk_bf16_f32 v0, v0, s0
	ds_write_b16 v11, v0 offset:54272
	v_mul_f32_e32 v0, v28, v7
	v_cvt_pk_bf16_f32 v0, v0, s0
	ds_write_b16 v11, v0 offset:54336
	v_mul_f32_e32 v0, v45, v8
	v_cvt_pk_bf16_f32 v0, v0, s0
	ds_write_b16 v11, v0 offset:54400
	v_mul_f32_e32 v0, v29, v8
	v_cvt_pk_bf16_f32 v0, v0, s0
	ds_write_b16 v11, v0 offset:54464
	v_mul_f32_e32 v0, v46, v9
	v_cvt_pk_bf16_f32 v0, v0, s0
	ds_write_b16 v11, v0 offset:54528
	v_mul_f32_e32 v0, v30, v9
	v_cvt_pk_bf16_f32 v0, v0, s0
	ds_write_b16 v11, v0 offset:54592
	v_mul_f32_e32 v0, v47, v10
	v_cvt_pk_bf16_f32 v0, v0, s0
	ds_write_b16 v11, v0 offset:54656
	v_mul_f32_e32 v0, v31, v10
	v_cvt_pk_bf16_f32 v0, v0, s0
	s_lshl_b64 s[2:3], s[12:13], 11
	ds_write_b16 v11, v0 offset:54720
	v_lshlrev_b32_e32 v0, 1, v207
	v_cvt_pk_bf16_f32 v32, v32, s0
	s_add_u32 s2, s34, s2
	v_and_b32_e32 v0, 0x70, v0
	ds_write_b16 v11, v32 offset:51200
	s_addc_u32 s3, s35, s3
	v_lshrrev_b32_e32 v14, 3, v206
	v_add_u32_e32 v15, s4, v0
	s_waitcnt lgkmcnt(0)
	v_lshl_add_u64 v[10:11], s[2:3], 0, v[0:1]
	v_lshl_add_u32 v0, v14, 7, v15
	v_or_b32_e32 v16, 8, v14
	ds_read_b128 v[2:5], v0 offset:51200
	v_lshl_add_u32 v6, v16, 7, v15
	ds_read_b128 v[6:9], v6 offset:51200
	v_lshlrev_b32_e32 v0, 11, v14
	v_lshl_add_u64 v[12:13], v[10:11], 0, v[0:1]
	v_lshlrev_b32_e32 v0, 11, v16
	s_waitcnt lgkmcnt(1)
	global_store_dwordx4 v[12:13], v[2:5], off
	s_mov_b64 s[4:5], 0
	s_and_b64 vcc, exec, s[14:15]
	v_lshl_add_u64 v[2:3], v[10:11], 0, v[0:1]
	v_or_b32_e32 v0, 16, v14
	s_waitcnt lgkmcnt(0)
	global_store_dwordx4 v[2:3], v[6:9], off
	v_lshl_add_u32 v2, v0, 7, v15
	v_or_b32_e32 v14, 24, v14
	ds_read_b128 v[2:5], v2 offset:51200
	v_lshl_add_u32 v6, v14, 7, v15
	ds_read_b128 v[6:9], v6 offset:51200
	v_lshlrev_b32_e32 v0, 11, v0
	v_lshl_add_u64 v[12:13], v[10:11], 0, v[0:1]
	v_lshlrev_b32_e32 v0, 11, v14
	s_waitcnt lgkmcnt(1)
	global_store_dwordx4 v[12:13], v[2:5], off
	s_nop 1
	v_lshl_add_u64 v[2:3], v[10:11], 0, v[0:1]
	s_waitcnt lgkmcnt(0)
; __device__ __forceinline__ int crow(int r,int hi){return (r&3)+8*(r>>2)+4*hi;}
; __device__ __forceinline__ int crow(int reg, int h) { return (reg & 3) + 8 * (reg >> 2) + 4 * h; }
; template<int THRL> __device__ __forceinline__ void attn_unit(int b,int colq,int colk,int colv,int colo,int qb,const bf16*Q,const bf16*__restrict__ K,const bf16*__restrict__ V,bf16*O,char*shm,const int tid_in){
;     ...
;   { bf16*stg=(bf16*)(shm+LDS_OST)+wid*2048;
;     #pragma unroll
;     for(int r=0;r<16;++r){const int orow=crow(r,hi);
;       #pragma unroll
;       for(int d0=0;d0<2;++d0)stg[orow*64+d0*32+r32]=__float2bfloat16(o[d0][r]*rli[r]);}
;     asm volatile("s_waitcnt lgkmcnt(0)":::"memory");
;     #pragma unroll
;     for(int i=0;i<4;++i){const int row=i*8+(lane>>3),ch=lane&7; const u32x4 v=*(const u32x4*)(stg+row*64+ch*8); ATTN_STORE16(Ow+(long)row*DMO+ch*8,v);} }
;   asm volatile("s_waitcnt lgkmcnt(0)\n\ts_barrier":::"memory");
	global_store_dwordx4 v[2:3], v[6:9], off
	s_waitcnt lgkmcnt(0)
	v_lshl_add_u32 v160, v246, 2, s37
	ds_read_b128 v[164:167], v160 offset:49280
	ds_read_b128 v[168:171], v160 offset:49312
	ds_read_b128 v[172:175], v160 offset:49344
	ds_read_b128 v[176:179], v160 offset:49376
	s_lshl_b32 s46, s36, 12
	v_lshlrev_b32_e32 v161, 1, v242
	v_lshlrev_b32_e32 v162, 9, v243
	v_add3_u32 v161, s46, v161, v162
	s_waitcnt lgkmcnt(0)
	v_rcp_f32_e32 v164, v164
	v_rcp_f32_e32 v165, v165
	v_rcp_f32_e32 v166, v166
	v_rcp_f32_e32 v167, v167
	v_rcp_f32_e32 v168, v168
	v_rcp_f32_e32 v169, v169
	v_rcp_f32_e32 v170, v170
	v_rcp_f32_e32 v171, v171
	v_rcp_f32_e32 v172, v172
	v_rcp_f32_e32 v173, v173
	v_rcp_f32_e32 v174, v174
	v_rcp_f32_e32 v175, v175
	v_rcp_f32_e32 v176, v176
	v_rcp_f32_e32 v177, v177
	v_rcp_f32_e32 v178, v178
	v_rcp_f32_e32 v179, v179
	s_nop 1
	v_mul_f32_e32 v180, v226, v164
	v_cvt_pk_bf16_f32 v180, v180, v180
	ds_write_b16 v161, v180 offset:51200
	v_mul_f32_e32 v181, v208, v164
	v_cvt_pk_bf16_f32 v181, v181, v181
	ds_write_b16 v161, v181 offset:51264
	v_mul_f32_e32 v180, v227, v165
	v_cvt_pk_bf16_f32 v180, v180, v180
	ds_write_b16 v161, v180 offset:51328
	v_mul_f32_e32 v181, v209, v165
	v_cvt_pk_bf16_f32 v181, v181, v181
	ds_write_b16 v161, v181 offset:51392
	v_mul_f32_e32 v180, v228, v166
	v_cvt_pk_bf16_f32 v180, v180, v180
	ds_write_b16 v161, v180 offset:51456
	v_mul_f32_e32 v181, v210, v166
	v_cvt_pk_bf16_f32 v181, v181, v181
	ds_write_b16 v161, v181 offset:51520
	v_mul_f32_e32 v180, v229, v167
	v_cvt_pk_bf16_f32 v180, v180, v180
	ds_write_b16 v161, v180 offset:51584
	v_mul_f32_e32 v181, v211, v167
	v_cvt_pk_bf16_f32 v181, v181, v181
	ds_write_b16 v161, v181 offset:51648
	v_mul_f32_e32 v180, v230, v168
	v_cvt_pk_bf16_f32 v180, v180, v180
	ds_write_b16 v161, v180 offset:52224
	v_mul_f32_e32 v181, v212, v168
	v_cvt_pk_bf16_f32 v181, v181, v181
	ds_write_b16 v161, v181 offset:52288
	v_mul_f32_e32 v180, v231, v169
	v_cvt_pk_bf16_f32 v180, v180, v180
	ds_write_b16 v161, v180 offset:52352
	v_mul_f32_e32 v181, v213, v169
	v_cvt_pk_bf16_f32 v181, v181, v181
	ds_write_b16 v161, v181 offset:52416
	v_mul_f32_e32 v180, v232, v170
	v_cvt_pk_bf16_f32 v180, v180, v180
	ds_write_b16 v161, v180 offset:52480
	v_mul_f32_e32 v181, v214, v170
	v_cvt_pk_bf16_f32 v181, v181, v181
	ds_write_b16 v161, v181 offset:52544
	v_mul_f32_e32 v180, v233, v171
	v_cvt_pk_bf16_f32 v180, v180, v180
	ds_write_b16 v161, v180 offset:52608
	v_mul_f32_e32 v181, v215, v171
	v_cvt_pk_bf16_f32 v181, v181, v181
	ds_write_b16 v161, v181 offset:52672
	v_mul_f32_e32 v180, v234, v172
	v_cvt_pk_bf16_f32 v180, v180, v180
	ds_write_b16 v161, v180 offset:53248
	v_mul_f32_e32 v181, v216, v172
	v_cvt_pk_bf16_f32 v181, v181, v181
	ds_write_b16 v161, v181 offset:53312
	v_mul_f32_e32 v180, v235, v173
	v_cvt_pk_bf16_f32 v180, v180, v180
	ds_write_b16 v161, v180 offset:53376
	v_mul_f32_e32 v181, v217, v173
	v_cvt_pk_bf16_f32 v181, v181, v181
	ds_write_b16 v161, v181 offset:53440
	v_mul_f32_e32 v180, v236, v174
	v_cvt_pk_bf16_f32 v180, v180, v180
	ds_write_b16 v161, v180 offset:53504
	v_mul_f32_e32 v181, v218, v174
	v_cvt_pk_bf16_f32 v181, v181, v181
	ds_write_b16 v161, v181 offset:53568
	v_mul_f32_e32 v180, v237, v175
	v_cvt_pk_bf16_f32 v180, v180, v180
	ds_write_b16 v161, v180 offset:53632
	v_mul_f32_e32 v181, v219, v175
	v_cvt_pk_bf16_f32 v181, v181, v181
	ds_write_b16 v161, v181 offset:53696
	v_mul_f32_e32 v180, v238, v176
	v_cvt_pk_bf16_f32 v180, v180, v180
	ds_write_b16 v161, v180 offset:54272
	v_mul_f32_e32 v181, v220, v176
	v_cvt_pk_bf16_f32 v181, v181, v181
	ds_write_b16 v161, v181 offset:54336
	v_mul_f32_e32 v180, v239, v177
	v_cvt_pk_bf16_f32 v180, v180, v180
	ds_write_b16 v161, v180 offset:54400
	v_mul_f32_e32 v181, v221, v177
	v_cvt_pk_bf16_f32 v181, v181, v181
	ds_write_b16 v161, v181 offset:54464
	v_mul_f32_e32 v180, v240, v178
	v_cvt_pk_bf16_f32 v180, v180, v180
	ds_write_b16 v161, v180 offset:54528
	v_mul_f32_e32 v181, v222, v178
	v_cvt_pk_bf16_f32 v181, v181, v181
	ds_write_b16 v161, v181 offset:54592
	v_mul_f32_e32 v180, v241, v179
	v_cvt_pk_bf16_f32 v180, v180, v180
	ds_write_b16 v161, v180 offset:54656
	v_mul_f32_e32 v181, v223, v179
	v_cvt_pk_bf16_f32 v181, v181, v181
	ds_write_b16 v161, v181 offset:54720
	s_waitcnt lgkmcnt(0)
	v_lshrrev_b32_e32 v182, 3, v206
	v_mov_b32_e32 v187, 0
	v_or_b32_e32 v183, 0, v182
	v_lshl_add_u32 v184, v183, 7, v15
	ds_read_b128 v[112:115], v184 offset:51200
	v_lshlrev_b32_e32 v186, 11, v183
	v_lshl_add_u64 v[128:129], v[10:11], 0, v[186:187]
	v_or_b32_e32 v183, 8, v182
	v_lshl_add_u32 v184, v183, 7, v15
	ds_read_b128 v[116:119], v184 offset:51200
	v_lshlrev_b32_e32 v186, 11, v183
	v_lshl_add_u64 v[130:131], v[10:11], 0, v[186:187]
	v_or_b32_e32 v183, 16, v182
	v_lshl_add_u32 v184, v183, 7, v15
	ds_read_b128 v[120:123], v184 offset:51200
	v_lshlrev_b32_e32 v186, 11, v183
	v_lshl_add_u64 v[132:133], v[10:11], 0, v[186:187]
	v_or_b32_e32 v183, 24, v182
	v_lshl_add_u32 v184, v183, 7, v15
	ds_read_b128 v[124:127], v184 offset:51200
	v_lshlrev_b32_e32 v186, 11, v183
	v_lshl_add_u64 v[134:135], v[10:11], 0, v[186:187]
	s_waitcnt lgkmcnt(3)
	global_store_dwordx4 v[128:129], v[112:115], off offset:128
	s_waitcnt lgkmcnt(2)
	global_store_dwordx4 v[130:131], v[116:119], off offset:128
	s_waitcnt lgkmcnt(1)
	global_store_dwordx4 v[132:133], v[120:123], off offset:128
	s_waitcnt lgkmcnt(0)
	global_store_dwordx4 v[134:135], v[124:127], off offset:128
	s_waitcnt lgkmcnt(0)
	s_barrier
	s_cbranch_vccnz .LBB0_235
; #define WAIT_BAR(N) asm volatile("s_waitcnt vmcnt(" #N ") lgkmcnt(0)\n\ts_barrier":::"memory")
;   #define DMA_K(t,slot) glds16(ksrc+(long)(t)*KVBLK*DM,(unsigned)__builtin_amdgcn_readfirstlane(kdst+(slot)))
;   #define DMA_V(t,slot) glds16(vsrc+(long)(t)*KVBLK*DM,(unsigned)__builtin_amdgcn_readfirstlane(vdst+(slot)))
;   #define CMASK(P0,P1,t) do{int jb_=(t)-(NT-4); if(jb_>=0)cmask(P0,P1,jb_,qrel,hi);}while(0)
;   #define CMASK(P0,P1,t) do{}while(0)
;   #define CMASK(P0,P1,t) do{int jb_=(t)-(NT-4); if(jb_>=0)cmask(P0,P1,jb_,qrel,hi);}while(0)
; template<int THRL> __device__ __forceinline__ void attn_unit(int b,int colq,int colk,int colv,int colo,int qb,const bf16*Q,const bf16*__restrict__ K,const bf16*__restrict__ V,bf16*O,char*shm,const int tid_in){
;   const int tid=tid_in,lane=tid&63,r32=lane&31,hi=lane>>5; const int wid=__builtin_amdgcn_readfirstlane(tid>>6);
;   const long rowbase=(long)b*SEQ; const int q0=qb*QB;
;   const bf16*Qw=Q+(rowbase+q0+wid*QBLK)*DM+colq;
;   const bf16*Kh=K+rowbase*DM+colk,*Vh=V+rowbase*DM+colv;
;   const unsigned lds0=(unsigned)(uintptr_t)shm;
;   float*wsf=(float*)(shm+LDS_WS)+wid*64;
;   const bf16*ksrc=Kh+(long)lane*DM+wid*8;
;   const bf16*vsrc=Vh+(long)(16*(wid&3)+(lane>>2))*DM+(wid>>2)*32+(lane&3)*8;
;   const unsigned kdst=lds0+LDS_K+wid*1024, vdst=lds0+LDS_V+wid*1024;
;     ...
;   const int vb0=(int)(lds0+LDS_V)+((lane>>4)&1)*32+(lane&3)*8+(4*hi+((lane&15)>>2))*64;
;   const char*Kbase=shm+LDS_K; bf16x8 kf[8];
;   const lds_cptr shm3=(lds_cptr)shm; const lds_cptr kp0=shm3+LDS_K+hi*1024+r32*16; const lds_cptr vp0=shm3+LDS_V+((lane>>4)&1)*32+(lane&3)*8+(4*hi+((lane&15)>>2))*64;
;   const int NT=(q0+QB)/KVBLK;
;   DMA_K(0,0);DMA_V(0,0);DMA_K(1,SLOTB);
;   bf16x8 qr[4];
;   #pragma unroll
;   for(int d0=0;d0<4;++d0)qr[d0]=*reinterpret_cast<const bf16x8*>(&Qw[(long)r32*DM+d0*16+hi*8]);
;   float mhat=0.f,l_reg=0.f;f32x16 o[2];o[0]=f32x16{};o[1]=f32x16{};f32x16 negm=f32x16{};asm volatile("":"+v"(negm));
;   const int qrel=wid*QBLK+r32;
;     ...
;   bool resc=false;
;     ...
;   f32x16 pA0,pA1,pB0,pB1;
;   int sl_prev=0,sl_cur=0,sl_next=SLOTB;
;     ...
;   DMA_K(2,2*SLOTB);
;   WAIT_BAR(3);
;   qkt(pA0,pA1,Kbase,qr,negm,r32,hi);asm volatile("s_nop 15\n\ts_nop 7":"+v"(pA0),"+v"(pA1));CMASK(pA0,pA1,0);
.LBB0_238:
	v_mbcnt_lo_u32_b32 v0, -1, 0
	v_mbcnt_hi_u32_b32 v0, -1, v0
	v_mov_b32_e32 v226, 0
	v_mov_b32_e32 v227, 0
	v_mov_b32_e32 v228, 0
	v_mov_b32_e32 v229, 0
	v_mov_b32_e32 v230, 0
	v_mov_b32_e32 v231, 0
	v_mov_b32_e32 v232, 0
	v_mov_b32_e32 v233, 0
	v_mov_b32_e32 v234, 0
	v_mov_b32_e32 v235, 0
	v_mov_b32_e32 v236, 0
	v_mov_b32_e32 v237, 0
	v_mov_b32_e32 v238, 0
	v_mov_b32_e32 v239, 0
	v_mov_b32_e32 v240, 0
	v_mov_b32_e32 v241, 0
	v_mov_b32_e32 v208, 0
	v_mov_b32_e32 v209, 0
	v_mov_b32_e32 v210, 0
	v_mov_b32_e32 v211, 0
	v_mov_b32_e32 v212, 0
	v_mov_b32_e32 v213, 0
	v_mov_b32_e32 v214, 0
	v_mov_b32_e32 v215, 0
	v_mov_b32_e32 v216, 0
	v_mov_b32_e32 v217, 0
	v_mov_b32_e32 v218, 0
	v_mov_b32_e32 v219, 0
	v_mov_b32_e32 v220, 0
	v_mov_b32_e32 v221, 0
	v_mov_b32_e32 v222, 0
	v_mov_b32_e32 v223, 0
	s_and_b64 s[2:3], s[4:5], exec
	v_add_u32_e32 v36, s33, v0
	s_cselect_b32 s18, s0, s1
	v_readfirstlane_b32 s15, v36
	s_ashr_i32 s36, s15, 6
	s_lshl_b32 s19, s18, 8
	s_lshl_b32 s20, s36, 5
	s_or_b32 s2, s6, s19
	s_ashr_i32 s3, s20, 31
	s_add_u32 s12, s2, s20
	s_addc_u32 s13, s7, s3
	v_and_b32_e32 v206, 63, v36
	s_mul_i32 s2, s13, 0x1c00
	s_mul_hi_u32 s3, s12, 0x1c00
	s_add_i32 s3, s3, s2
	s_mul_i32 s2, s12, 0x1c00
	v_mul_u32_u24_e32 v0, 0xe00, v206
	s_add_u32 s2, s30, s2
	v_lshlrev_b32_e32 v0, 1, v0
	s_addc_u32 s3, s31, s3
	v_lshl_add_u64 v[2:3], s[8:9], 0, v[0:1]
	s_lshl_b32 s16, s36, 3
	s_lshl_b32 s14, s36, 4
	v_bfe_u32 v0, v36, 2, 4
	s_ashr_i32 s17, s16, 31
	v_and_or_b32 v0, s14, 48, v0
	v_lshl_add_u64 v[16:17], s[16:17], 1, v[2:3]
	s_mov_b64 s[16:17], 0x400
	v_mul_u32_u24_e32 v0, 0xe00, v0
	s_ashr_i32 s14, s15, 3
	v_lshl_add_u64 v[196:197], v[16:17], 0, s[16:17]
	v_lshlrev_b32_e32 v0, 1, v0
	s_and_b32 s16, s14, 0xffffffe0
	v_lshlrev_b32_e32 v207, 3, v36
	v_lshl_add_u64 v[2:3], s[10:11], 0, v[0:1]
	s_ashr_i32 s17, s16, 31
	v_and_b32_e32 v244, 24, v207
	v_lshl_add_u64 v[2:3], s[16:17], 1, v[2:3]
	v_lshlrev_b32_e32 v0, 1, v244
	s_lshl_b32 s14, s36, 10
	v_lshl_add_u64 v[2:3], v[2:3], 0, v[0:1]
	s_mov_b64 s[16:17], 0x800
	s_cmp_lg_u32 0, -1
	v_lshl_add_u64 v[34:35], v[2:3], 0, s[16:17]
	s_cselect_b32 s16, 0, 0
	v_and_b32_e32 v242, 31, v36
	s_add_i32 s38, s14, s16
	s_mov_b32 s16, m0
	s_mov_b32 m0, s38
	s_nop 0
	global_load_lds_dwordx4 v[196:197], off
	s_mov_b32 m0, s16
	s_add_i32 s39, s38, 0x6000
	s_mov_b32 s16, m0
	s_mov_b32 m0, s39
	s_nop 0
	global_load_lds_dwordx4 v[34:35], off
	s_mov_b32 m0, s16
	s_add_i32 s46, s39, 0xe780
	s_mov_b32 s47, m0
	s_mov_b32 m0, s46
	s_nop 0
	global_load_lds_dwordx4 v[34:35], off offset:128
	s_mov_b32 m0, s47
	v_mul_u32_u24_e32 v0, 0xe00, v242
	v_bfe_u32 v243, v36, 5, 1
	s_mov_b64 s[16:17], 0x70400
	v_lshlrev_b32_e32 v0, 1, v0
	v_lshl_add_u64 v[2:3], v[16:17], 0, s[16:17]
	s_add_i32 s16, s38, 0x2000
	s_mov_b32 s17, m0
	s_mov_b32 m0, s16
	s_nop 0
	global_load_lds_dwordx4 v[2:3], off
	s_mov_b32 m0, s17
	v_lshl_or_b32 v0, v243, 4, v0
	global_load_dwordx4 v[148:151], v0, s[2:3]
	global_load_dwordx4 v[140:143], v0, s[2:3] offset:32
	global_load_dwordx4 v[132:135], v0, s[2:3] offset:64
	global_load_dwordx4 v[128:131], v0, s[2:3] offset:96
	v_mov_b32_e32 v2, v1
	v_mov_b32_e32 v3, v1
	v_mov_b32_e32 v4, v1
	v_mov_b32_e32 v5, v1
	v_mov_b32_e32 v6, v1
	v_mov_b32_e32 v7, v1
	v_mov_b32_e32 v8, v1
	v_mov_b32_e32 v9, v1
	v_mov_b32_e32 v10, v1
	v_mov_b32_e32 v11, v1
	v_mov_b32_e32 v12, v1
	v_mov_b32_e32 v13, v1
	v_mov_b32_e32 v14, v1
	v_mov_b32_e32 v15, v1
	v_lshlrev_b32_e32 v0, 10, v243
	v_lshlrev_b32_e32 v18, 4, v242
	s_mov_b64 s[2:3], 0xe0400
	v_add3_u32 v253, 0, v0, v18
	v_lshl_add_u64 v[18:19], v[16:17], 0, s[2:3]
	v_mov_b32_e32 v0, v1
	v_mov_b64_e32 v[16:17], v[14:15]
	v_mov_b64_e32 v[14:15], v[12:13]
	v_mov_b64_e32 v[12:13], v[10:11]
	v_mov_b64_e32 v[10:11], v[8:9]
	v_mov_b64_e32 v[8:9], v[6:7]
	v_mov_b64_e32 v[6:7], v[4:5]
	v_mov_b64_e32 v[4:5], v[2:3]
	v_mov_b64_e32 v[2:3], v[0:1]
	s_add_i32 s2, s38, 0x4000
	s_mov_b32 s3, m0
	s_mov_b32 m0, s2
	s_nop 0
	global_load_lds_dwordx4 v[18:19], off
	s_mov_b32 m0, s3
	s_waitcnt vmcnt(3) lgkmcnt(0)
	s_barrier
	ds_read_b128 v[38:41], v253
	s_cmp_lg_u32 s18, 0
	s_cselect_b64 s[2:3], -1, 0
	v_lshlrev_b32_e32 v246, 2, v243
	v_or_b32_e32 v251, s20, v242
	s_and_b64 vcc, exec, s[2:3]
	s_waitcnt vmcnt(3) lgkmcnt(0)
	v_mfma_f32_32x32x16_bf16 v[18:33], v[38:41], v[148:151], v[2:17]
	ds_read_b128 v[38:41], v253 offset:512
	s_waitcnt lgkmcnt(0)
	v_mfma_f32_32x32x16_bf16 v[2:17], v[38:41], v[148:151], v[2:17]
	ds_read_b128 v[38:41], v253 offset:2048
	s_waitcnt vmcnt(2) lgkmcnt(0)
	v_mfma_f32_32x32x16_bf16 v[18:33], v[38:41], v[140:143], v[18:33]
	ds_read_b128 v[38:41], v253 offset:2560
	s_waitcnt lgkmcnt(0)
	v_mfma_f32_32x32x16_bf16 v[2:17], v[38:41], v[140:143], v[2:17]
	ds_read_b128 v[38:41], v253 offset:4096
	s_waitcnt vmcnt(1) lgkmcnt(0)
	v_mfma_f32_32x32x16_bf16 v[18:33], v[38:41], v[132:135], v[18:33]
	ds_read_b128 v[38:41], v253 offset:4608
	s_waitcnt lgkmcnt(0)
	v_mfma_f32_32x32x16_bf16 v[2:17], v[38:41], v[132:135], v[2:17]
	ds_read_b128 v[38:41], v253 offset:6144
	s_waitcnt vmcnt(0) lgkmcnt(0)
	v_mfma_f32_32x32x16_bf16 v[18:33], v[38:41], v[128:131], v[18:33]
	ds_read_b128 v[38:41], v253 offset:6656
	s_waitcnt lgkmcnt(0)
	v_mfma_f32_32x32x16_bf16 v[2:17], v[38:41], v[128:131], v[2:17]
	s_nop 15
	s_nop 7
	s_cbranch_vccnz .LBB0_240
; __device__ __forceinline__ float max3f(float a,float b,float c){float r;asm("v_max3_f32 %0, %1, %2, %3":"=v"(r):"v"(a),"v"(b),"v"(c));return r;}
; __device__ __forceinline__ float max2f(float a,float b){float r;asm("v_max_f32_e32 %0, %1, %2":"=v"(r):"v"(a),"v"(b));return r;}
; __device__ __forceinline__ void cmask(f32x16&p0,f32x16&p1,int jb,int qrel,int hi){
;   const float NEG=-INFINITY; int kb=64*jb+4*hi;
;   #pragma unroll
;   for(int r=0;r<16;++r){int kv=kb+(r&3)+8*(r>>2); if(kv>qrel)p0[r]=NEG; if(kv+32>qrel)p1[r]=NEG;}
; }
; __device__ __forceinline__ float rowmax(const f32x16&p0,const f32x16&p1){
;   float a=max3f(p0[0],p0[1],p1[0]),b=max3f(p0[2],p0[3],p1[1]);a=max3f(a,p1[2],p1[3]);
;   #pragma unroll
;   for(int r=4;r<16;r+=4){a=max3f(a,p0[r],p0[r+1]);b=max3f(b,p0[r+2],p0[r+3]);a=max3f(a,p1[r],p1[r+1]);b=max3f(b,p1[r+2],p1[r+3]);}
;   const float m=max2f(a,b);
;   auto rr=__builtin_amdgcn_permlane32_swap(__float_as_uint(m),__float_as_uint(m),false,false);
;   return max2f(__uint_as_float(rr[0]),__uint_as_float(rr[1]));
	v_or_b32_e32 v0, 32, v246
	v_cmp_le_i32_e32 vcc, v0, v251
	v_or_b32_e32 v0, 33, v246
	s_nop 7
	v_cndmask_b32_e32 v2, v248, v2, vcc
	v_cmp_lt_i32_e32 vcc, v246, v251
	s_nop 1
	v_cndmask_b32_e32 v19, v248, v19, vcc
	v_cmp_le_i32_e32 vcc, v246, v251
	s_nop 1
	v_cndmask_b32_e32 v18, v248, v18, vcc
	v_cmp_le_i32_e32 vcc, v0, v251
	v_or_b32_e32 v0, 2, v246
	s_nop 0
	v_cndmask_b32_e32 v3, v248, v3, vcc
	v_cmp_le_i32_e32 vcc, v0, v251
	v_or_b32_e32 v0, 34, v246
	s_nop 0
	v_cndmask_b32_e32 v20, v248, v20, vcc
	v_cmp_le_i32_e32 vcc, v0, v251
	v_or_b32_e32 v0, 3, v246
	s_nop 0
	v_cndmask_b32_e32 v4, v248, v4, vcc
	v_cmp_le_i32_e32 vcc, v0, v251
	v_or_b32_e32 v0, 35, v246
	s_nop 0
	v_cndmask_b32_e32 v21, v248, v21, vcc
	v_cmp_le_i32_e32 vcc, v0, v251
	v_or_b32_e32 v0, 8, v246
	s_nop 0
	v_cndmask_b32_e32 v5, v248, v5, vcc
	v_cmp_le_i32_e32 vcc, v0, v251
	v_or_b32_e32 v0, 40, v246
	s_nop 0
	v_cndmask_b32_e32 v22, v248, v22, vcc
	v_cmp_le_i32_e32 vcc, v0, v251
	v_or_b32_e32 v0, 9, v246
	s_nop 0
	v_cndmask_b32_e32 v6, v248, v6, vcc
	v_cmp_le_i32_e32 vcc, v0, v251
	v_or_b32_e32 v0, 41, v246
	s_nop 0
	v_cndmask_b32_e32 v23, v248, v23, vcc
	v_cmp_le_i32_e32 vcc, v0, v251
	v_or_b32_e32 v0, 10, v246
	s_nop 0
	v_cndmask_b32_e32 v7, v248, v7, vcc
	v_cmp_le_i32_e32 vcc, v0, v251
	v_or_b32_e32 v0, 42, v246
	s_nop 0
	v_cndmask_b32_e32 v24, v248, v24, vcc
	v_cmp_le_i32_e32 vcc, v0, v251
	v_or_b32_e32 v0, 11, v246
	s_nop 0
	v_cndmask_b32_e32 v8, v248, v8, vcc
	v_cmp_le_i32_e32 vcc, v0, v251
	v_or_b32_e32 v0, 43, v246
	s_nop 0
	v_cndmask_b32_e32 v25, v248, v25, vcc
	v_cmp_le_i32_e32 vcc, v0, v251
	v_or_b32_e32 v0, 16, v246
	s_nop 0
	v_cndmask_b32_e32 v9, v248, v9, vcc
	v_cmp_le_i32_e32 vcc, v0, v251
	v_or_b32_e32 v0, 48, v246
	s_nop 0
	v_cndmask_b32_e32 v26, v248, v26, vcc
	v_cmp_le_i32_e32 vcc, v0, v251
	v_or_b32_e32 v0, 17, v246
	s_nop 0
	v_cndmask_b32_e32 v10, v248, v10, vcc
	v_cmp_le_i32_e32 vcc, v0, v251
	v_or_b32_e32 v0, 49, v246
	s_nop 0
	v_cndmask_b32_e32 v27, v248, v27, vcc
	v_cmp_le_i32_e32 vcc, v0, v251
	v_or_b32_e32 v0, 18, v246
	s_nop 0
	v_cndmask_b32_e32 v11, v248, v11, vcc
	v_cmp_le_i32_e32 vcc, v0, v251
	v_or_b32_e32 v0, 50, v246
	s_nop 0
	v_cndmask_b32_e32 v28, v248, v28, vcc
	v_cmp_le_i32_e32 vcc, v0, v251
	v_or_b32_e32 v0, 19, v246
	s_nop 0
	v_cndmask_b32_e32 v12, v248, v12, vcc
	v_cmp_le_i32_e32 vcc, v0, v251
	v_or_b32_e32 v0, 51, v246
	s_nop 0
	v_cndmask_b32_e32 v29, v248, v29, vcc
	v_cmp_le_i32_e32 vcc, v0, v251
	v_or_b32_e32 v0, 24, v246
	s_nop 0
	v_cndmask_b32_e32 v13, v248, v13, vcc
	v_cmp_le_i32_e32 vcc, v0, v251
	v_or_b32_e32 v0, 56, v246
	s_nop 0
	v_cndmask_b32_e32 v30, v248, v30, vcc
	v_cmp_le_i32_e32 vcc, v0, v251
	v_or_b32_e32 v0, 25, v246
	s_nop 0
	v_cndmask_b32_e32 v14, v248, v14, vcc
	v_cmp_le_i32_e32 vcc, v0, v251
	v_or_b32_e32 v0, 57, v246
	s_nop 0
	v_cndmask_b32_e32 v31, v248, v31, vcc
	v_cmp_le_i32_e32 vcc, v0, v251
	v_or_b32_e32 v0, 26, v246
	s_nop 0
	v_cndmask_b32_e32 v15, v248, v15, vcc
	v_cmp_le_i32_e32 vcc, v0, v251
	v_or_b32_e32 v0, 58, v246
	s_nop 0
	v_cndmask_b32_e32 v32, v248, v32, vcc
	v_cmp_le_i32_e32 vcc, v0, v251
	v_or_b32_e32 v0, 27, v246
	s_nop 0
	v_cndmask_b32_e32 v16, v248, v16, vcc
	v_cmp_le_i32_e32 vcc, v0, v251
	v_or_b32_e32 v0, 59, v246
	s_nop 0
	v_cndmask_b32_e32 v33, v248, v33, vcc
	v_cmp_le_i32_e32 vcc, v0, v251
	s_nop 1
	v_cndmask_b32_e32 v17, v248, v17, vcc
.LBB0_240:
	v_lshlrev_b32_e32 v0, 1, v36
	v_and_b32_e32 v247, 32, v0
	v_lshlrev_b32_e32 v0, 4, v36
	v_and_b32_e32 v0, 0xc0, v0
	v_lshl_or_b32 v245, v243, 8, v0
	v_add_u32_e32 v0, 0, v247
	v_add3_u32 v254, v0, v244, v245
	v_max3_f32 v0, v18, v19, v2
	v_max3_f32 v36, v20, v21, v3
	s_and_b32 s15, s15, 0x3fffffc0
	v_max3_f32 v0, v0, v4, v5
	v_max3_f32 v36, v36, v24, v25
	s_add_i32 s17, s19, 0x100
	v_max3_f32 v0, v0, v22, v23
	v_max3_f32 v36, v36, v8, v9
	s_lshl_b32 s15, s15, 2
	v_max3_f32 v0, v0, v6, v7
	v_max3_f32 v36, v36, v28, v29
	s_add_i32 s37, s15, 0
	v_max3_f32 v0, v0, v26, v27
	v_max3_f32 v36, v36, v12, v13
	s_lshr_b32 s40, s17, 6
	v_max3_f32 v0, v0, v10, v11
	v_max3_f32 v36, v36, v32, v33
	s_cmp_lg_u32 0, -1
	v_max3_f32 v0, v0, v30, v31
	v_max3_f32 v36, v36, v16, v17
	v_lshl_add_u64 v[198:199], v[34:35], 0, s[96:97]
	v_max3_f32 v0, v0, v14, v15
	s_mov_b32 s16, 1
	v_max_f32_e32 v0, v0, v36
	s_mov_b32 s20, 0
	v_mov_b32_e32 v36, v0
	s_nop 1
	v_permlane32_swap_b32_e32 v0, v36
	v_max_f32_e32 v0, v0, v36
	v_lshlrev_b32_e32 v255, 4, v243
	v_add_f32_e32 v252, v1, v0
	v_sub_f32_e32 v2, v2, v0
	v_sub_f32_e32 v3, v3, v0
	v_sub_f32_e32 v18, v18, v0
	v_sub_f32_e32 v19, v19, v0
	v_sub_f32_e32 v20, v20, v0
	s_nop 0
	v_xor_b32_e32 v48, 0x80000000, v252
	v_mov_b32_e32 v49, v48
	v_mov_b32_e32 v50, v48
	v_mov_b32_e32 v51, v48
	v_mov_b32_e32 v52, v48
	v_mov_b32_e32 v53, v48
	v_mov_b32_e32 v54, v48
	v_mov_b32_e32 v55, v48
	v_mov_b32_e32 v56, v48
	v_mov_b32_e32 v57, v48
	v_mov_b32_e32 v58, v48
	v_mov_b32_e32 v59, v48
	v_mov_b32_e32 v60, v48
	v_mov_b32_e32 v61, v48
	v_mov_b32_e32 v62, v48
	v_mov_b32_e32 v63, v48
	s_waitcnt vmcnt(0) lgkmcnt(0)
	s_barrier
; #define WAIT_BAR(N) asm volatile("s_waitcnt vmcnt(" #N ") lgkmcnt(0)\n\ts_barrier":::"memory")
;   #define DMA_K(t,slot) glds16(ksrc+(long)(t)*KVBLK*DM,(unsigned)__builtin_amdgcn_readfirstlane(kdst+(slot)))
;   #define DMA_V(t,slot) glds16(vsrc+(long)(t)*KVBLK*DM,(unsigned)__builtin_amdgcn_readfirstlane(vdst+(slot)))
;   #define ROT() do{sl_prev=sl_cur;sl_cur=sl_next;sl_next=(sl_next==(NSLOT-1)*SLOTB)?0:sl_next+SLOTB;}while(0)
; template<int THRL> __device__ __forceinline__ void attn_unit(int b,int colq,int colk,int colv,int colo,int qb,const bf16*Q,const bf16*__restrict__ K,const bf16*__restrict__ V,bf16*O,char*shm,const int tid_in){
;     ...
;   _Pragma("unroll") for(int r=0;r<16;++r)pA1[r]=__builtin_amdgcn_exp2f(pA1[r]);
;   WAIT_BAR(0);
;   DMA_K(3,0);DMA_V(1,SLOTB);
;   ROT();
;   kload8(kf,kp0+sl_cur);
;   WAIT_BAR(2);
	v_exp_f32_e32 v64, v2
	v_exp_f32_e32 v65, v3
	v_lshl_add_u64 v[2:3], v[196:197], 0, s[60:61]
	s_mov_b32 s15, m0
	s_mov_b32 m0, s38
	s_nop 0
	global_load_lds_dwordx4 v[2:3], off
	s_mov_b32 m0, s15
	s_cselect_b32 s15, 0, 0
	s_add_i32 s14, s15, s14
	s_add_i32 s14, s14, 0x8000
	s_mov_b32 s15, m0
	s_mov_b32 m0, s14
	s_nop 0
	global_load_lds_dwordx4 v[198:199], off
	s_mov_b32 m0, s15
	s_add_i32 s46, s14, 0xe780
	s_mov_b32 s47, m0
	s_mov_b32 m0, s46
	s_nop 0
	global_load_lds_dwordx4 v[198:199], off offset:128
	s_mov_b32 m0, s47
	ds_read_b128 v[188:191], v253 offset:8192
	ds_read_b128 v[184:187], v253 offset:8704
	ds_read_b128 v[180:183], v253 offset:10240
	ds_read_b128 v[176:179], v253 offset:10752
	ds_read_b128 v[172:175], v253 offset:12288
	ds_read_b128 v[168:171], v253 offset:12800
	ds_read_b128 v[164:167], v253 offset:14336
	ds_read_b128 v[160:163], v253 offset:14848
	v_sub_f32_e32 v4, v4, v0
	v_sub_f32_e32 v21, v21, v0
	v_sub_f32_e32 v5, v5, v0
	v_sub_f32_e32 v22, v22, v0
	v_sub_f32_e32 v6, v6, v0
	v_sub_f32_e32 v23, v23, v0
	v_sub_f32_e32 v7, v7, v0
	v_sub_f32_e32 v24, v24, v0
	v_sub_f32_e32 v8, v8, v0
	v_sub_f32_e32 v25, v25, v0
	v_sub_f32_e32 v9, v9, v0
	v_sub_f32_e32 v26, v26, v0
	v_sub_f32_e32 v10, v10, v0
	v_sub_f32_e32 v27, v27, v0
	v_sub_f32_e32 v11, v11, v0
	v_sub_f32_e32 v28, v28, v0
	v_sub_f32_e32 v12, v12, v0
	v_sub_f32_e32 v29, v29, v0
	v_sub_f32_e32 v13, v13, v0
	v_sub_f32_e32 v30, v30, v0
	v_sub_f32_e32 v14, v14, v0
	v_sub_f32_e32 v31, v31, v0
	v_sub_f32_e32 v15, v15, v0
	v_sub_f32_e32 v32, v32, v0
	v_sub_f32_e32 v16, v16, v0
	v_sub_f32_e32 v33, v33, v0
	v_sub_f32_e32 v0, v17, v0
	v_exp_f32_e32 v80, v18
	v_exp_f32_e32 v81, v19
	v_exp_f32_e32 v82, v20
	v_exp_f32_e32 v83, v21
	v_exp_f32_e32 v84, v22
	v_exp_f32_e32 v85, v23
	v_exp_f32_e32 v86, v24
	v_exp_f32_e32 v87, v25
	v_exp_f32_e32 v88, v26
	v_exp_f32_e32 v89, v27
	v_exp_f32_e32 v90, v28
	v_exp_f32_e32 v91, v29
	v_exp_f32_e32 v92, v30
	v_exp_f32_e32 v93, v31
	v_exp_f32_e32 v94, v32
	v_exp_f32_e32 v95, v33
	v_exp_f32_e32 v66, v4
	v_exp_f32_e32 v67, v5
	v_exp_f32_e32 v68, v6
	v_exp_f32_e32 v69, v7
	v_exp_f32_e32 v70, v8
	v_exp_f32_e32 v71, v9
	v_exp_f32_e32 v72, v10
	v_exp_f32_e32 v73, v11
	v_exp_f32_e32 v74, v12
	v_exp_f32_e32 v75, v13
	v_exp_f32_e32 v76, v14
	v_exp_f32_e32 v77, v15
	v_exp_f32_e32 v78, v16
	v_exp_f32_e32 v79, v0
	s_waitcnt vmcnt(2) lgkmcnt(0)
	s_barrier
	s_andn2_b64 vcc, exec, s[2:3]
	v_cmp_gt_u32_e64 s[2:3], 32, v206
	v_lshl_add_u32 v250, v242, 2, s37
	s_cbranch_vccnz .LBB0_256
	v_mov_b32_e32 v14, v1
	v_mov_b32_e32 v15, v1
	v_lshl_add_u64 v[200:201], v[34:35], 0, s[60:61]
	s_mov_b64 s[14:15], 0x230000
	v_mov_b32_e32 v0, v1
	v_mov_b32_e32 v2, v1
	v_mov_b32_e32 v3, v1
	v_mov_b32_e32 v4, v1
	v_mov_b32_e32 v5, v1
	v_mov_b32_e32 v6, v1
	v_mov_b32_e32 v7, v1
	v_mov_b32_e32 v8, v1
	v_mov_b32_e32 v9, v1
	v_mov_b32_e32 v10, v1
	v_mov_b32_e32 v11, v1
	v_mov_b32_e32 v12, v1
	v_mov_b32_e32 v13, v1
	v_mov_b64_e32 v[46:47], v[14:15]
	v_mov_b64_e32 v[30:31], v[14:15]
	v_lshl_add_u64 v[202:203], v[196:197], 0, s[14:15]
	s_mov_b32 s14, 0
	s_movk_i32 s20, 0x4000
	s_movk_i32 s22, 0x2000
	v_mov_b32_e32 v224, 0
	s_mov_b32 s21, 6
	v_mov_b64_e32 v[44:45], v[12:13]
	v_mov_b64_e32 v[42:43], v[10:11]
	v_mov_b64_e32 v[40:41], v[8:9]
	v_mov_b64_e32 v[38:39], v[6:7]
	v_mov_b64_e32 v[36:37], v[4:5]
	v_mov_b64_e32 v[34:35], v[2:3]
	v_mov_b64_e32 v[32:33], v[0:1]
	v_mov_b64_e32 v[28:29], v[12:13]
	v_mov_b64_e32 v[26:27], v[10:11]
	v_mov_b64_e32 v[24:25], v[8:9]
	v_mov_b64_e32 v[22:23], v[6:7]
	v_mov_b64_e32 v[20:21], v[4:5]
	v_mov_b64_e32 v[18:19], v[2:3]
	v_mov_b64_e32 v[16:17], v[0:1]
.LBB0_242:
	v_add_u32_e32 v0, s14, v254
	s_add_i32 s45, s14, 0xe800
	ds_read_b64_tr_b16 v[192:193], v0 offset:24576
	ds_read_b64_tr_b16 v[194:195], v0 offset:25088
	s_waitcnt lgkmcnt(9)
	v_mfma_f32_32x32x16_bf16 v[112:127], v[188:191], v[148:151], v[48:63]
	v_add_f32_e32 v2, v80, v81
	v_add_f32_e32 v2, v82, v2
	v_add_f32_e32 v2, v83, v2
	v_add_f32_e32 v2, v84, v2
	v_add_f32_e32 v2, v85, v2
	v_cvt_pk_bf16_f32 v156, v80, v81
	v_cvt_pk_bf16_f32 v157, v82, v83
	ds_read_b64_tr_b16 v[80:81], v0 offset:28672
	ds_read_b64_tr_b16 v[82:83], v0 offset:29184
	s_waitcnt lgkmcnt(10)
	v_mfma_f32_32x32x16_bf16 v[96:111], v[184:187], v[148:151], v[48:63]
	v_add_f32_e32 v2, v86, v2
	v_add_f32_e32 v2, v87, v2
	v_add_f32_e32 v2, v88, v2
	v_add_f32_e32 v6, v89, v2
	v_cvt_pk_bf16_f32 v158, v84, v85
	v_cvt_pk_bf16_f32 v159, v86, v87
	ds_read_b64_tr_b16 v[2:3], v0 offset:25600
	ds_read_b64_tr_b16 v[4:5], v0 offset:26112
	s_waitcnt lgkmcnt(11)
	v_mfma_f32_32x32x16_bf16 v[112:127], v[180:183], v[140:143], v[112:127]
	v_add_f32_e32 v6, v90, v6
	v_add_f32_e32 v6, v91, v6
	v_add_f32_e32 v6, v92, v6
	v_add_f32_e32 v10, v93, v6
	v_cvt_pk_bf16_f32 v152, v88, v89
	v_cvt_pk_bf16_f32 v153, v90, v91
	ds_read_b64_tr_b16 v[6:7], v0 offset:29696
	ds_read_b64_tr_b16 v[8:9], v0 offset:30208
	s_waitcnt lgkmcnt(12)
	v_mfma_f32_32x32x16_bf16 v[96:111], v[176:179], v[140:143], v[96:111]
	v_add_f32_e32 v10, v94, v10
	v_add_f32_e32 v10, v95, v10
	v_add_f32_e32 v10, v64, v10
	v_add_f32_e32 v14, v65, v10
	v_cvt_pk_bf16_f32 v154, v92, v93
	v_cvt_pk_bf16_f32 v155, v94, v95
	ds_read_b64_tr_b16 v[10:11], v0 offset:26624
	ds_read_b64_tr_b16 v[12:13], v0 offset:27136
	s_waitcnt lgkmcnt(13)
	v_mfma_f32_32x32x16_bf16 v[112:127], v[172:175], v[132:135], v[112:127]
	v_add_f32_e32 v14, v66, v14
	v_add_f32_e32 v14, v67, v14
	v_add_f32_e32 v14, v68, v14
	v_add_f32_e32 v14, v69, v14
	v_cvt_pk_bf16_f32 v144, v64, v65
	v_cvt_pk_bf16_f32 v145, v66, v67
	ds_read_b64_tr_b16 v[64:65], v0 offset:30720
	ds_read_b64_tr_b16 v[66:67], v0 offset:31232
	s_waitcnt lgkmcnt(14)
	v_mfma_f32_32x32x16_bf16 v[96:111], v[168:171], v[132:135], v[96:111]
	v_add_f32_e32 v14, v70, v14
	v_add_f32_e32 v14, v71, v14
	v_add_f32_e32 v14, v72, v14
	v_add_f32_e32 v14, v73, v14
	v_cvt_pk_bf16_f32 v146, v68, v69
	v_cvt_pk_bf16_f32 v147, v70, v71
	ds_read_b64_tr_b16 v[68:69], v0 offset:27648
	ds_read_b64_tr_b16 v[70:71], v0 offset:28160
	s_waitcnt lgkmcnt(14)
	v_mfma_f32_32x32x16_bf16 v[112:127], v[164:167], v[128:131], v[112:127]
	v_add_f32_e32 v14, v74, v14
	v_add_f32_e32 v14, v75, v14
	v_add_f32_e32 v14, v76, v14
	v_add_f32_e32 v14, v77, v14
	v_cvt_pk_bf16_f32 v136, v72, v73
	v_cvt_pk_bf16_f32 v137, v74, v75
	ds_read_b64_tr_b16 v[72:73], v0 offset:31744
	ds_read_b64_tr_b16 v[74:75], v0 offset:32256
	v_mfma_f32_32x32x16_bf16 v[96:111], v[160:163], v[128:131], v[96:111]
	v_add_f32_e32 v0, v78, v14
	v_add_f32_e32 v0, v79, v0
	v_add_f32_e32 v0, 0, v0
	v_cvt_pk_bf16_f32 v138, v76, v77
	v_cvt_pk_bf16_f32 v139, v78, v79
	v_lshl_add_u64 v[14:15], v[202:203], 0, s[86:87]
	s_add_i32 s14, s22, s38
	s_mov_b32 s15, m0
	s_mov_b32 m0, s14
	s_nop 0
	global_load_lds_dwordx4 v[14:15], off
	s_mov_b32 m0, s15
	v_lshl_add_u64 v[14:15], v[200:201], 0, s[86:87]
	s_add_i32 s14, s20, s39
	s_mov_b32 s15, m0
	s_mov_b32 m0, s14
	s_nop 0
	global_load_lds_dwordx4 v[14:15], off
	s_mov_b32 m0, s15
	s_add_i32 s46, s14, 0xe780
	s_mov_b32 s47, m0
	s_mov_b32 m0, s46
	s_nop 0
	global_load_lds_dwordx4 v[14:15], off offset:128
	s_mov_b32 m0, s47
	v_max_f32_e32 v14, v113, v113
	v_max_f32_e32 v15, v112, v112
	v_max_f32_e32 v14, v15, v14
	v_max3_f32 v15, v114, v115, v97
	v_max3_f32 v14, v14, v96, v98
	v_max3_f32 v14, v14, v99, v116
	v_max3_f32 v15, v15, v118, v119
	v_max3_f32 v14, v14, v117, v100
	v_max3_f32 v15, v15, v102, v103
	v_max3_f32 v14, v14, v101, v120
	v_max3_f32 v15, v15, v122, v123
	v_max3_f32 v14, v14, v121, v104
	v_max3_f32 v15, v15, v106, v107
	v_max3_f32 v14, v14, v105, v124
	v_max3_f32 v15, v15, v126, v127
	v_max3_f32 v76, v14, v125, v108
	v_max3_f32 v15, v15, v110, v111
	v_add_f32_e32 v14, v224, v0
	v_max3_f32 v0, v76, v109, v15
	v_mov_b32_e32 v15, v0
	s_nop 1
	v_permlane32_swap_b32_e32 v0, v15
	v_max_f32_e32 v15, v15, v15
	v_max_f32_e32 v0, v0, v0
	v_max_f32_e32 v0, v0, v15
	v_cmp_lt_f32_e32 vcc, s91, v0
	s_cmp_lg_u64 vcc, 0
	s_cselect_b64 s[14:15], -1, 0
	s_cbranch_vccnz .LBB0_250
.LBB0_243:
	v_add_u32_e32 v0, s45, v254
	s_waitcnt lgkmcnt(14)
	v_mfma_f32_32x32x16_bf16 v[32:47], v[156:159], v[192:195], v[32:47]
	v_exp_f32_e32 v112, v112
	v_exp_f32_e32 v113, v113
	ds_read_b64_tr_b16 v[192:193], v0 offset:24576
	ds_read_b64_tr_b16 v[194:195], v0 offset:25088
	s_waitcnt lgkmcnt(14)
	v_mfma_f32_32x32x16_bf16 v[16:31], v[156:159], v[80:83], v[16:31]
	v_exp_f32_e32 v114, v114
	v_exp_f32_e32 v115, v115
	ds_read_b64_tr_b16 v[80:81], v0 offset:28672
	ds_read_b64_tr_b16 v[82:83], v0 offset:29184
	s_waitcnt lgkmcnt(14)
	v_mfma_f32_32x32x16_bf16 v[32:47], v[152:155], v[2:5], v[32:47]
	v_exp_f32_e32 v116, v116
	v_exp_f32_e32 v117, v117
	ds_read_b64_tr_b16 v[2:3], v0 offset:25600
	ds_read_b64_tr_b16 v[4:5], v0 offset:26112
	s_waitcnt lgkmcnt(14)
	v_mfma_f32_32x32x16_bf16 v[16:31], v[152:155], v[6:9], v[16:31]
	v_exp_f32_e32 v118, v118
	v_exp_f32_e32 v119, v119
	ds_read_b64_tr_b16 v[6:7], v0 offset:29696
	ds_read_b64_tr_b16 v[8:9], v0 offset:30208
	s_waitcnt lgkmcnt(14)
	v_mfma_f32_32x32x16_bf16 v[32:47], v[144:147], v[10:13], v[32:47]
	v_exp_f32_e32 v120, v120
	v_exp_f32_e32 v121, v121
	ds_read_b64_tr_b16 v[10:11], v0 offset:26624
	ds_read_b64_tr_b16 v[12:13], v0 offset:27136
	s_waitcnt lgkmcnt(14)
	v_mfma_f32_32x32x16_bf16 v[16:31], v[144:147], v[64:67], v[16:31]
	v_exp_f32_e32 v122, v122
	v_exp_f32_e32 v123, v123
	ds_read_b64_tr_b16 v[64:65], v0 offset:30720
	ds_read_b64_tr_b16 v[66:67], v0 offset:31232
	s_waitcnt lgkmcnt(14)
	v_mfma_f32_32x32x16_bf16 v[32:47], v[136:139], v[68:71], v[32:47]
	v_exp_f32_e32 v124, v124
	v_exp_f32_e32 v125, v125
	ds_read_b64_tr_b16 v[68:69], v0 offset:27648
	ds_read_b64_tr_b16 v[70:71], v0 offset:28160
	s_waitcnt lgkmcnt(14)
	v_mfma_f32_32x32x16_bf16 v[16:31], v[136:139], v[72:75], v[16:31]
	v_exp_f32_e32 v126, v126
	v_exp_f32_e32 v127, v127
	ds_read_b64_tr_b16 v[72:73], v0 offset:31744
	ds_read_b64_tr_b16 v[74:75], v0 offset:32256
	s_waitcnt lgkmcnt(14)
	v_mfma_f32_32x32x16_bf16 v[226:241], v[156:159], v[192:195], v[226:241]
	v_exp_f32_e32 v96, v96
	v_exp_f32_e32 v97, v97
	s_waitcnt lgkmcnt(12)
	v_mfma_f32_32x32x16_bf16 v[208:223], v[156:159], v[80:83], v[208:223]
	v_exp_f32_e32 v98, v98
	v_exp_f32_e32 v99, v99
	v_add_u32_e32 v0, s20, v253
	ds_read_b128 v[76:79], v0
	ds_read_b128 v[184:187], v0 offset:512
	s_waitcnt lgkmcnt(12)
	v_mfma_f32_32x32x16_bf16 v[226:241], v[152:155], v[2:5], v[226:241]
	v_exp_f32_e32 v100, v100
	v_exp_f32_e32 v101, v101
	ds_read_b128 v[188:191], v0 offset:2048
	ds_read_b128 v[180:183], v0 offset:2560
	s_waitcnt lgkmcnt(12)
	v_mfma_f32_32x32x16_bf16 v[208:223], v[152:155], v[6:9], v[208:223]
	v_exp_f32_e32 v102, v102
	v_exp_f32_e32 v103, v103
	ds_read_b128 v[176:179], v0 offset:4096
	ds_read_b128 v[172:175], v0 offset:4608
	s_waitcnt lgkmcnt(12)
	v_mfma_f32_32x32x16_bf16 v[226:241], v[144:147], v[10:13], v[226:241]
	v_exp_f32_e32 v104, v104
	v_exp_f32_e32 v105, v105
	ds_read_b128 v[168:171], v0 offset:6144
	ds_read_b128 v[164:167], v0 offset:6656
	s_waitcnt lgkmcnt(12)
	v_mfma_f32_32x32x16_bf16 v[208:223], v[144:147], v[64:67], v[208:223]
	v_exp_f32_e32 v106, v106
	v_exp_f32_e32 v107, v107
	s_waitcnt lgkmcnt(10)
	v_mfma_f32_32x32x16_bf16 v[226:241], v[136:139], v[68:71], v[226:241]
	v_exp_f32_e32 v108, v108
	v_exp_f32_e32 v109, v109
	s_waitcnt lgkmcnt(8)
	v_mfma_f32_32x32x16_bf16 v[208:223], v[136:139], v[72:75], v[208:223]
	v_exp_f32_e32 v110, v110
	v_exp_f32_e32 v111, v111
	s_waitcnt vmcnt(2) lgkmcnt(0)
	s_barrier
	s_andn2_b64 vcc, exec, s[14:15]
	v_add_u32_e32 v0, s37, v255
	s_cbranch_vccnz .LBB0_245
	s_waitcnt lgkmcnt(0)
	ds_read_b128 v[2:5], v0 offset:49248
	ds_read_b128 v[6:9], v0 offset:49216
	ds_read_b128 v[10:13], v0 offset:49184
	ds_read_b128 v[64:67], v0 offset:49152
	s_waitcnt lgkmcnt(3)
	v_pk_mul_f32 v[44:45], v[44:45], v[2:3]
	s_waitcnt lgkmcnt(2)
	v_pk_mul_f32 v[40:41], v[40:41], v[6:7]
	s_waitcnt lgkmcnt(1)
	v_pk_mul_f32 v[36:37], v[36:37], v[10:11]
	v_pk_mul_f32 v[46:47], v[46:47], v[4:5]
	v_pk_mul_f32 v[42:43], v[42:43], v[8:9]
	v_pk_mul_f32 v[38:39], v[38:39], v[12:13]
	s_waitcnt lgkmcnt(0)
	v_pk_mul_f32 v[34:35], v[34:35], v[66:67]
	v_pk_mul_f32 v[32:33], v[32:33], v[64:65]
	v_pk_mul_f32 v[28:29], v[28:29], v[2:3]
	v_pk_mul_f32 v[24:25], v[24:25], v[6:7]
	v_pk_mul_f32 v[20:21], v[20:21], v[10:11]
	v_pk_mul_f32 v[30:31], v[30:31], v[4:5]
	v_pk_mul_f32 v[26:27], v[26:27], v[8:9]
	v_pk_mul_f32 v[22:23], v[22:23], v[12:13]
	v_pk_mul_f32 v[18:19], v[18:19], v[66:67]
	v_pk_mul_f32 v[16:17], v[16:17], v[64:65]
	v_pk_mul_f32 v[238:239], v[238:239], v[2:3]
	v_pk_mul_f32 v[234:235], v[234:235], v[6:7]
	v_pk_mul_f32 v[230:231], v[230:231], v[10:11]
	v_pk_mul_f32 v[240:241], v[240:241], v[4:5]
	v_pk_mul_f32 v[236:237], v[236:237], v[8:9]
	v_pk_mul_f32 v[232:233], v[232:233], v[12:13]
	v_pk_mul_f32 v[228:229], v[228:229], v[66:67]
	v_pk_mul_f32 v[226:227], v[226:227], v[64:65]
	v_pk_mul_f32 v[220:221], v[220:221], v[2:3]
	v_pk_mul_f32 v[216:217], v[216:217], v[6:7]
	v_pk_mul_f32 v[212:213], v[212:213], v[10:11]
	v_pk_mul_f32 v[222:223], v[222:223], v[4:5]
	v_pk_mul_f32 v[218:219], v[218:219], v[8:9]
	v_pk_mul_f32 v[214:215], v[214:215], v[12:13]
	v_pk_mul_f32 v[210:211], v[210:211], v[66:67]
	v_pk_mul_f32 v[208:209], v[208:209], v[64:65]
.LBB0_245:
	s_add_i32 s14, s20, 0x2000
	s_cmpk_lg_i32 s20, 0x4000
	s_cselect_b32 s41, s14, 0
	v_add_u32_e32 v15, s22, v254
	s_add_i32 s45, s22, 0xe800
	ds_read_b64_tr_b16 v[160:161], v15 offset:24576
	ds_read_b64_tr_b16 v[162:163], v15 offset:25088
	s_waitcnt lgkmcnt(9)
	v_mfma_f32_32x32x16_bf16 v[80:95], v[76:79], v[148:151], v[48:63]
	v_add_f32_e32 v2, v112, v113
	v_add_f32_e32 v2, v114, v2
	v_add_f32_e32 v2, v115, v2
	v_add_f32_e32 v2, v116, v2
	v_add_f32_e32 v2, v117, v2
	v_cvt_pk_bf16_f32 v156, v112, v113
	v_cvt_pk_bf16_f32 v157, v114, v115
	ds_read_b64_tr_b16 v[112:113], v15 offset:28672
	ds_read_b64_tr_b16 v[114:115], v15 offset:29184
	s_waitcnt lgkmcnt(10)
	v_mfma_f32_32x32x16_bf16 v[64:79], v[184:187], v[148:151], v[48:63]
	v_add_f32_e32 v2, v118, v2
	v_add_f32_e32 v2, v119, v2
	v_add_f32_e32 v2, v120, v2
	v_add_f32_e32 v6, v121, v2
	v_cvt_pk_bf16_f32 v158, v116, v117
	v_cvt_pk_bf16_f32 v159, v118, v119
	ds_read_b64_tr_b16 v[2:3], v15 offset:25600
	ds_read_b64_tr_b16 v[4:5], v15 offset:26112
	s_waitcnt lgkmcnt(11)
	v_mfma_f32_32x32x16_bf16 v[80:95], v[188:191], v[140:143], v[80:95]
	v_add_f32_e32 v6, v122, v6
	v_add_f32_e32 v6, v123, v6
	v_add_f32_e32 v6, v124, v6
	v_add_f32_e32 v10, v125, v6
	v_cvt_pk_bf16_f32 v152, v120, v121
	v_cvt_pk_bf16_f32 v153, v122, v123
	ds_read_b64_tr_b16 v[6:7], v15 offset:29696
	ds_read_b64_tr_b16 v[8:9], v15 offset:30208
	s_waitcnt lgkmcnt(12)
	v_mfma_f32_32x32x16_bf16 v[64:79], v[180:183], v[140:143], v[64:79]
	v_add_f32_e32 v10, v126, v10
	v_add_f32_e32 v10, v127, v10
	v_add_f32_e32 v10, v96, v10
	v_add_f32_e32 v116, v97, v10
	v_cvt_pk_bf16_f32 v154, v124, v125
	v_cvt_pk_bf16_f32 v155, v126, v127
	ds_read_b64_tr_b16 v[10:11], v15 offset:26624
	ds_read_b64_tr_b16 v[12:13], v15 offset:27136
	s_waitcnt lgkmcnt(13)
	v_mfma_f32_32x32x16_bf16 v[80:95], v[176:179], v[132:135], v[80:95]
	v_add_f32_e32 v116, v98, v116
	v_add_f32_e32 v116, v99, v116
	v_add_f32_e32 v116, v100, v116
	v_add_f32_e32 v116, v101, v116
	v_cvt_pk_bf16_f32 v144, v96, v97
	v_cvt_pk_bf16_f32 v145, v98, v99
	ds_read_b64_tr_b16 v[96:97], v15 offset:30720
	ds_read_b64_tr_b16 v[98:99], v15 offset:31232
	s_waitcnt lgkmcnt(14)
	v_mfma_f32_32x32x16_bf16 v[64:79], v[172:175], v[132:135], v[64:79]
	v_add_f32_e32 v116, v102, v116
	v_add_f32_e32 v116, v103, v116
	v_add_f32_e32 v116, v104, v116
	v_add_f32_e32 v116, v105, v116
	v_cvt_pk_bf16_f32 v146, v100, v101
	v_cvt_pk_bf16_f32 v147, v102, v103
	ds_read_b64_tr_b16 v[100:101], v15 offset:27648
	ds_read_b64_tr_b16 v[102:103], v15 offset:28160
	s_waitcnt lgkmcnt(14)
	v_mfma_f32_32x32x16_bf16 v[80:95], v[168:171], v[128:131], v[80:95]
	v_add_f32_e32 v116, v106, v116
	v_add_f32_e32 v116, v107, v116
	v_add_f32_e32 v116, v108, v116
	v_add_f32_e32 v116, v109, v116
	v_cvt_pk_bf16_f32 v136, v104, v105
	v_cvt_pk_bf16_f32 v137, v106, v107
	ds_read_b64_tr_b16 v[104:105], v15 offset:31744
	ds_read_b64_tr_b16 v[106:107], v15 offset:32256
	v_mfma_f32_32x32x16_bf16 v[64:79], v[164:167], v[128:131], v[64:79]
	v_add_f32_e32 v15, v110, v116
	v_add_f32_e32 v15, v111, v15
	v_add_f32_e32 v15, 0, v15
	v_cvt_pk_bf16_f32 v138, v108, v109
	v_cvt_pk_bf16_f32 v139, v110, v111
	v_max_f32_e32 v108, v81, v81
	v_max_f32_e32 v109, v80, v80
	v_max_f32_e32 v108, v109, v108
	s_nop 3
	v_max3_f32 v109, v82, v83, v65
	v_max3_f32 v108, v108, v64, v66
	v_max3_f32 v108, v108, v67, v84
	v_max3_f32 v109, v109, v86, v87
	v_max3_f32 v108, v108, v85, v68
	v_max3_f32 v109, v109, v70, v71
	v_max3_f32 v108, v108, v69, v88
	v_max3_f32 v109, v109, v90, v91
	v_max3_f32 v108, v108, v89, v72
	v_max3_f32 v109, v109, v74, v75
	v_max3_f32 v108, v108, v73, v92
	v_max3_f32 v109, v109, v94, v95
	v_max3_f32 v108, v108, v93, v76
	v_max3_f32 v109, v109, v78, v79
	v_add_f32_e32 v224, v14, v15
	v_max3_f32 v14, v108, v77, v109
	v_mov_b32_e32 v15, v14
	s_nop 1
	v_permlane32_swap_b32_e32 v14, v15
	v_max_f32_e32 v15, v15, v15
	v_max_f32_e32 v14, v14, v14
	s_add_i32 s14, s20, s38
	s_mov_b32 s15, m0
	s_mov_b32 m0, s14
	s_nop 0
	global_load_lds_dwordx4 v[202:203], off
	s_mov_b32 m0, s15
	v_max_f32_e32 v14, v14, v15
	s_add_i32 s14, s41, s39
	s_mov_b32 s15, m0
	s_mov_b32 m0, s14
	s_nop 0
	global_load_lds_dwordx4 v[200:201], off
	s_mov_b32 m0, s15
	s_add_i32 s46, s14, 0xe780
	s_mov_b32 s47, m0
	s_mov_b32 m0, s46
	s_nop 0
	global_load_lds_dwordx4 v[200:201], off offset:128
	s_mov_b32 m0, s47
	v_cmp_lt_f32_e32 vcc, s91, v14
	s_cmp_lg_u64 vcc, 0
	s_cselect_b64 s[14:15], -1, 0
	s_cbranch_vccnz .LBB0_253
.LBB0_246:
	v_add_u32_e32 v14, s45, v254
	s_waitcnt lgkmcnt(14)
	v_mfma_f32_32x32x16_bf16 v[32:47], v[156:159], v[160:163], v[32:47]
	v_exp_f32_e32 v80, v80
	v_exp_f32_e32 v81, v81
	ds_read_b64_tr_b16 v[160:161], v14 offset:24576
	ds_read_b64_tr_b16 v[162:163], v14 offset:25088
	s_waitcnt lgkmcnt(14)
	v_mfma_f32_32x32x16_bf16 v[16:31], v[156:159], v[112:115], v[16:31]
	v_exp_f32_e32 v82, v82
	v_exp_f32_e32 v83, v83
	ds_read_b64_tr_b16 v[112:113], v14 offset:28672
	ds_read_b64_tr_b16 v[114:115], v14 offset:29184
	s_waitcnt lgkmcnt(14)
	v_mfma_f32_32x32x16_bf16 v[32:47], v[152:155], v[2:5], v[32:47]
	v_exp_f32_e32 v84, v84
	v_exp_f32_e32 v85, v85
	ds_read_b64_tr_b16 v[2:3], v14 offset:25600
	ds_read_b64_tr_b16 v[4:5], v14 offset:26112
	s_waitcnt lgkmcnt(14)
	v_mfma_f32_32x32x16_bf16 v[16:31], v[152:155], v[6:9], v[16:31]
	v_exp_f32_e32 v86, v86
	v_exp_f32_e32 v87, v87
	ds_read_b64_tr_b16 v[6:7], v14 offset:29696
	ds_read_b64_tr_b16 v[8:9], v14 offset:30208
	s_waitcnt lgkmcnt(14)
	v_mfma_f32_32x32x16_bf16 v[32:47], v[144:147], v[10:13], v[32:47]
	v_exp_f32_e32 v88, v88
	v_exp_f32_e32 v89, v89
	ds_read_b64_tr_b16 v[10:11], v14 offset:26624
	ds_read_b64_tr_b16 v[12:13], v14 offset:27136
	s_waitcnt lgkmcnt(14)
	v_mfma_f32_32x32x16_bf16 v[16:31], v[144:147], v[96:99], v[16:31]
	v_exp_f32_e32 v90, v90
	v_exp_f32_e32 v91, v91
	ds_read_b64_tr_b16 v[96:97], v14 offset:30720
	ds_read_b64_tr_b16 v[98:99], v14 offset:31232
	s_waitcnt lgkmcnt(14)
	v_mfma_f32_32x32x16_bf16 v[32:47], v[136:139], v[100:103], v[32:47]
	v_exp_f32_e32 v92, v92
	v_exp_f32_e32 v93, v93
	ds_read_b64_tr_b16 v[100:101], v14 offset:27648
	ds_read_b64_tr_b16 v[102:103], v14 offset:28160
	s_waitcnt lgkmcnt(14)
	v_mfma_f32_32x32x16_bf16 v[16:31], v[136:139], v[104:107], v[16:31]
	v_exp_f32_e32 v94, v94
	v_exp_f32_e32 v95, v95
	ds_read_b64_tr_b16 v[104:105], v14 offset:31744
	ds_read_b64_tr_b16 v[106:107], v14 offset:32256
	s_waitcnt lgkmcnt(14)
	v_mfma_f32_32x32x16_bf16 v[226:241], v[156:159], v[160:163], v[226:241]
	v_exp_f32_e32 v64, v64
	v_exp_f32_e32 v65, v65
	s_waitcnt lgkmcnt(12)
	v_mfma_f32_32x32x16_bf16 v[208:223], v[156:159], v[112:115], v[208:223]
	v_exp_f32_e32 v66, v66
	v_exp_f32_e32 v67, v67
	v_add_u32_e32 v14, s41, v253
	ds_read_b128 v[188:191], v14
	ds_read_b128 v[184:187], v14 offset:512
	s_waitcnt lgkmcnt(12)
	v_mfma_f32_32x32x16_bf16 v[226:241], v[152:155], v[2:5], v[226:241]
	v_exp_f32_e32 v68, v68
	v_exp_f32_e32 v69, v69
	ds_read_b128 v[180:183], v14 offset:2048
	ds_read_b128 v[176:179], v14 offset:2560
	s_waitcnt lgkmcnt(12)
	v_mfma_f32_32x32x16_bf16 v[208:223], v[152:155], v[6:9], v[208:223]
	v_exp_f32_e32 v70, v70
	v_exp_f32_e32 v71, v71
	ds_read_b128 v[172:175], v14 offset:4096
	ds_read_b128 v[168:171], v14 offset:4608
	s_waitcnt lgkmcnt(12)
	v_mfma_f32_32x32x16_bf16 v[226:241], v[144:147], v[10:13], v[226:241]
	v_exp_f32_e32 v72, v72
	v_exp_f32_e32 v73, v73
	ds_read_b128 v[164:167], v14 offset:6144
	ds_read_b128 v[160:163], v14 offset:6656
	s_waitcnt lgkmcnt(12)
	v_mfma_f32_32x32x16_bf16 v[208:223], v[144:147], v[96:99], v[208:223]
	v_exp_f32_e32 v74, v74
	v_exp_f32_e32 v75, v75
	s_waitcnt lgkmcnt(10)
	v_mfma_f32_32x32x16_bf16 v[226:241], v[136:139], v[100:103], v[226:241]
	v_exp_f32_e32 v76, v76
	v_exp_f32_e32 v77, v77
	s_waitcnt lgkmcnt(8)
	v_mfma_f32_32x32x16_bf16 v[208:223], v[136:139], v[104:107], v[208:223]
	v_exp_f32_e32 v78, v78
	v_exp_f32_e32 v79, v79
	s_waitcnt vmcnt(2) lgkmcnt(0)
	s_barrier
	s_andn2_b64 vcc, exec, s[14:15]
	s_cbranch_vccnz .LBB0_248
	s_waitcnt lgkmcnt(0)
	ds_read_b128 v[2:5], v0 offset:49248
	ds_read_b128 v[6:9], v0 offset:49216
	ds_read_b128 v[10:13], v0 offset:49184
	ds_read_b128 v[96:99], v0 offset:49152
	s_waitcnt lgkmcnt(3)
	v_pk_mul_f32 v[44:45], v[44:45], v[2:3]
	s_waitcnt lgkmcnt(2)
	v_pk_mul_f32 v[40:41], v[40:41], v[6:7]
	s_waitcnt lgkmcnt(1)
	v_pk_mul_f32 v[36:37], v[36:37], v[10:11]
	v_pk_mul_f32 v[46:47], v[46:47], v[4:5]
	v_pk_mul_f32 v[42:43], v[42:43], v[8:9]
	v_pk_mul_f32 v[38:39], v[38:39], v[12:13]
	s_waitcnt lgkmcnt(0)
	v_pk_mul_f32 v[34:35], v[34:35], v[98:99]
	v_pk_mul_f32 v[32:33], v[32:33], v[96:97]
	v_pk_mul_f32 v[28:29], v[28:29], v[2:3]
	v_pk_mul_f32 v[24:25], v[24:25], v[6:7]
	v_pk_mul_f32 v[20:21], v[20:21], v[10:11]
	v_pk_mul_f32 v[30:31], v[30:31], v[4:5]
	v_pk_mul_f32 v[26:27], v[26:27], v[8:9]
	v_pk_mul_f32 v[22:23], v[22:23], v[12:13]
	v_pk_mul_f32 v[18:19], v[18:19], v[98:99]
	v_pk_mul_f32 v[16:17], v[16:17], v[96:97]
	v_pk_mul_f32 v[238:239], v[238:239], v[2:3]
	v_pk_mul_f32 v[234:235], v[234:235], v[6:7]
	v_pk_mul_f32 v[230:231], v[230:231], v[10:11]
	v_pk_mul_f32 v[240:241], v[240:241], v[4:5]
	v_pk_mul_f32 v[236:237], v[236:237], v[8:9]
	v_pk_mul_f32 v[232:233], v[232:233], v[12:13]
	v_pk_mul_f32 v[228:229], v[228:229], v[98:99]
	v_pk_mul_f32 v[226:227], v[226:227], v[96:97]
	v_pk_mul_f32 v[220:221], v[220:221], v[2:3]
	v_pk_mul_f32 v[216:217], v[216:217], v[6:7]
	v_pk_mul_f32 v[212:213], v[212:213], v[10:11]
	v_pk_mul_f32 v[222:223], v[222:223], v[4:5]
	v_pk_mul_f32 v[218:219], v[218:219], v[8:9]
	v_pk_mul_f32 v[214:215], v[214:215], v[12:13]
	v_pk_mul_f32 v[210:211], v[210:211], v[98:99]
	v_pk_mul_f32 v[208:209], v[208:209], v[96:97]

.LBB0_250:
	v_max_f32_e32 v0, v0, v0
	v_max_f32_e32 v0, 0, v0
	v_exp_f32_e64 v15, -v0
	v_add_f32_e32 v252, v252, v0
	v_xor_b32_e32 v48, 0x80000000, v252
	v_mov_b32_e32 v49, v48
	v_mov_b32_e32 v50, v48
	v_mov_b32_e32 v51, v48
	v_mov_b32_e32 v52, v48
	v_mov_b32_e32 v53, v48
	v_mov_b32_e32 v54, v48
	v_mov_b32_e32 v55, v48
	v_mov_b32_e32 v56, v48
	v_mov_b32_e32 v57, v48
	v_mov_b32_e32 v58, v48
	v_mov_b32_e32 v59, v48
	v_mov_b32_e32 v60, v48
	v_mov_b32_e32 v61, v48
	v_mov_b32_e32 v62, v48
	v_mov_b32_e32 v63, v48
	s_and_saveexec_b64 s[16:17], s[2:3]
	ds_write_b32 v250, v15 offset:49152
	s_or_b64 exec, exec, s[16:17]
	v_sub_f32_e32 v127, v127, v0
	v_sub_f32_e32 v126, v126, v0
	v_sub_f32_e32 v125, v125, v0
	v_sub_f32_e32 v124, v124, v0
	v_sub_f32_e32 v123, v123, v0
	v_sub_f32_e32 v122, v122, v0
	v_sub_f32_e32 v121, v121, v0
	v_sub_f32_e32 v120, v120, v0
	v_sub_f32_e32 v119, v119, v0
	v_sub_f32_e32 v118, v118, v0
	v_sub_f32_e32 v117, v117, v0
	v_sub_f32_e32 v116, v116, v0
	v_sub_f32_e32 v115, v115, v0
	v_sub_f32_e32 v114, v114, v0
	v_sub_f32_e32 v113, v113, v0
	v_sub_f32_e32 v112, v112, v0
	v_sub_f32_e32 v111, v111, v0
	v_sub_f32_e32 v110, v110, v0
	v_sub_f32_e32 v109, v109, v0
	v_sub_f32_e32 v108, v108, v0
	v_sub_f32_e32 v107, v107, v0
	v_sub_f32_e32 v106, v106, v0
	v_sub_f32_e32 v105, v105, v0
	v_sub_f32_e32 v104, v104, v0
	v_sub_f32_e32 v103, v103, v0
	v_sub_f32_e32 v102, v102, v0
	v_sub_f32_e32 v101, v101, v0
	v_sub_f32_e32 v100, v100, v0
	v_sub_f32_e32 v99, v99, v0
	v_sub_f32_e32 v98, v98, v0
	v_sub_f32_e32 v97, v97, v0
	v_sub_f32_e32 v96, v96, v0
	v_mul_f32_e32 v14, v14, v15
	s_branch .LBB0_243
.LBB0_253:
	v_max_f32_e32 v14, v14, v14
	v_max_f32_e32 v14, 0, v14
	v_exp_f32_e64 v15, -v14
	v_add_f32_e32 v252, v252, v14
	v_xor_b32_e32 v48, 0x80000000, v252
	v_mov_b32_e32 v49, v48
	v_mov_b32_e32 v50, v48
	v_mov_b32_e32 v51, v48
	v_mov_b32_e32 v52, v48
	v_mov_b32_e32 v53, v48
	v_mov_b32_e32 v54, v48
	v_mov_b32_e32 v55, v48
	v_mov_b32_e32 v56, v48
	v_mov_b32_e32 v57, v48
	v_mov_b32_e32 v58, v48
	v_mov_b32_e32 v59, v48
	v_mov_b32_e32 v60, v48
	v_mov_b32_e32 v61, v48
	v_mov_b32_e32 v62, v48
	v_mov_b32_e32 v63, v48
	s_and_saveexec_b64 s[16:17], s[2:3]
	ds_write_b32 v250, v15 offset:49152
	s_or_b64 exec, exec, s[16:17]
	v_sub_f32_e32 v95, v95, v14
	v_sub_f32_e32 v94, v94, v14
	v_sub_f32_e32 v93, v93, v14
	v_sub_f32_e32 v92, v92, v14
	v_sub_f32_e32 v91, v91, v14
	v_sub_f32_e32 v90, v90, v14
	v_sub_f32_e32 v89, v89, v14
	v_sub_f32_e32 v88, v88, v14
	v_sub_f32_e32 v87, v87, v14
	v_sub_f32_e32 v86, v86, v14
	v_sub_f32_e32 v85, v85, v14
	v_sub_f32_e32 v84, v84, v14
	v_sub_f32_e32 v83, v83, v14
	v_sub_f32_e32 v82, v82, v14
	v_sub_f32_e32 v81, v81, v14
	v_sub_f32_e32 v80, v80, v14
	v_sub_f32_e32 v79, v79, v14
	v_sub_f32_e32 v78, v78, v14
	v_sub_f32_e32 v77, v77, v14
	v_sub_f32_e32 v76, v76, v14
	v_sub_f32_e32 v75, v75, v14
	v_sub_f32_e32 v74, v74, v14
	v_sub_f32_e32 v73, v73, v14
	v_sub_f32_e32 v72, v72, v14
	v_sub_f32_e32 v71, v71, v14
	v_sub_f32_e32 v70, v70, v14
	v_sub_f32_e32 v69, v69, v14
	v_sub_f32_e32 v68, v68, v14
	v_sub_f32_e32 v67, v67, v14
	v_sub_f32_e32 v66, v66, v14
	v_sub_f32_e32 v65, v65, v14
	v_sub_f32_e32 v64, v64, v14
	v_mul_f32_e32 v224, v224, v15
	s_branch .LBB0_246

; __device__ __forceinline__ void cmask(f32x16&p0,f32x16&p1,int jb,int qrel,int hi){
;   const float NEG=-INFINITY; int kb=64*jb+4*hi;
;   #pragma unroll
;   for(int r=0;r<16;++r){int kv=kb+(r&3)+8*(r>>2); if(kv>qrel)p0[r]=NEG; if(kv+32>qrel)p1[r]=NEG;}
; }
.LBB0_258:
	v_add_u32_e32 v0, s42, v254
	s_add_i32 s45, s42, 0xe800
	ds_read_b64_tr_b16 v[6:7], v0 offset:24576
	ds_read_b64_tr_b16 v[8:9], v0 offset:25088
	v_add_f32_e32 v2, v80, v81
	v_add_f32_e32 v2, v82, v2
	v_add_f32_e32 v2, v83, v2
	v_add_f32_e32 v2, v84, v2
	v_add_f32_e32 v10, v85, v2
	v_cvt_pk_bf16_f32 v156, v80, v81
	v_cvt_pk_bf16_f32 v157, v82, v83
	s_waitcnt lgkmcnt(9)
	v_mfma_f32_32x32x16_bf16 v[96:111], v[188:191], v[148:151], v[48:63]
	ds_read_b64_tr_b16 v[2:3], v0 offset:28672
	ds_read_b64_tr_b16 v[4:5], v0 offset:29184
	s_waitcnt lgkmcnt(10)
	v_mfma_f32_32x32x16_bf16 v[48:63], v[184:187], v[148:151], v[48:63]
	v_add_f32_e32 v10, v86, v10
	v_add_f32_e32 v10, v87, v10
	v_add_f32_e32 v10, v88, v10
	v_add_f32_e32 v14, v89, v10
	v_cvt_pk_bf16_f32 v158, v84, v85
	v_cvt_pk_bf16_f32 v159, v86, v87
	ds_read_b64_tr_b16 v[10:11], v0 offset:25600
	ds_read_b64_tr_b16 v[12:13], v0 offset:26112
	v_add_f32_e32 v14, v90, v14
	v_add_f32_e32 v14, v91, v14
	v_add_f32_e32 v14, v92, v14
	v_add_f32_e32 v14, v93, v14
	v_cvt_pk_bf16_f32 v152, v88, v89
	v_cvt_pk_bf16_f32 v153, v90, v91
	s_waitcnt lgkmcnt(11)
	v_mfma_f32_32x32x16_bf16 v[96:111], v[180:183], v[140:143], v[96:111]
	ds_read_b64_tr_b16 v[112:113], v0 offset:29696
	ds_read_b64_tr_b16 v[114:115], v0 offset:30208
	s_waitcnt lgkmcnt(12)
	v_mfma_f32_32x32x16_bf16 v[48:63], v[176:179], v[140:143], v[48:63]
	v_add_f32_e32 v14, v94, v14
	v_add_f32_e32 v14, v95, v14
	v_add_f32_e32 v14, v64, v14
	v_add_f32_e32 v14, v65, v14
	v_cvt_pk_bf16_f32 v154, v92, v93
	v_cvt_pk_bf16_f32 v155, v94, v95
	ds_read_b64_tr_b16 v[116:117], v0 offset:26624
	ds_read_b64_tr_b16 v[118:119], v0 offset:27136
	v_add_f32_e32 v14, v66, v14
	v_add_f32_e32 v14, v67, v14
	v_add_f32_e32 v14, v68, v14
	v_add_f32_e32 v14, v69, v14
	v_cvt_pk_bf16_f32 v144, v64, v65
	v_cvt_pk_bf16_f32 v145, v66, v67
	s_waitcnt lgkmcnt(13)
	v_mfma_f32_32x32x16_bf16 v[96:111], v[172:175], v[132:135], v[96:111]
	ds_read_b64_tr_b16 v[120:121], v0 offset:30720
	ds_read_b64_tr_b16 v[122:123], v0 offset:31232
	s_waitcnt lgkmcnt(14)
	v_mfma_f32_32x32x16_bf16 v[48:63], v[168:171], v[132:135], v[48:63]
	v_add_f32_e32 v14, v70, v14
	v_add_f32_e32 v14, v71, v14
	v_add_f32_e32 v14, v72, v14
	v_add_f32_e32 v14, v73, v14
	v_cvt_pk_bf16_f32 v146, v68, v69
	v_cvt_pk_bf16_f32 v147, v70, v71
	ds_read_b64_tr_b16 v[124:125], v0 offset:27648
	ds_read_b64_tr_b16 v[126:127], v0 offset:28160
	v_add_f32_e32 v14, v74, v14
	v_add_f32_e32 v14, v75, v14
	v_add_f32_e32 v14, v76, v14
	v_add_f32_e32 v14, v77, v14
	v_cvt_pk_bf16_f32 v136, v72, v73
	v_cvt_pk_bf16_f32 v137, v74, v75
	s_waitcnt lgkmcnt(14)
	v_mfma_f32_32x32x16_bf16 v[96:111], v[164:167], v[128:131], v[96:111]
	ds_read_b64_tr_b16 v[132:133], v0 offset:31744
	ds_read_b64_tr_b16 v[134:135], v0 offset:32256
	v_mfma_f32_32x32x16_bf16 v[48:63], v[160:163], v[128:131], v[48:63]
	v_add_f32_e32 v0, v78, v14
	v_add_f32_e32 v0, v79, v0
	v_add_f32_e32 v0, 0, v0
	v_cvt_pk_bf16_f32 v138, v76, v77
	v_cvt_pk_bf16_f32 v139, v78, v79
	v_or_b32_e32 v15, 0xe0, v246
	v_or_b32_e32 v14, 0xc0, v246
	v_cmp_le_i32_e32 vcc, v15, v251
	v_add_f32_e32 v0, v224, v0
	s_nop 2
	v_cndmask_b32_e32 v48, v248, v48, vcc
	v_cmp_lt_i32_e32 vcc, v14, v251
	s_nop 1
	v_cndmask_b32_e32 v65, v248, v97, vcc
	v_cmp_le_i32_e32 vcc, v14, v251
	v_or_b32_e32 v14, 0xe1, v246
	s_nop 0
	v_cndmask_b32_e32 v64, v248, v96, vcc
	v_cmp_le_i32_e32 vcc, v14, v251
	v_or_b32_e32 v14, 0xc2, v246
	v_max_f32_e32 v15, v64, v64
	v_cndmask_b32_e32 v49, v248, v49, vcc
	v_cmp_le_i32_e32 vcc, v14, v251
	v_or_b32_e32 v14, 0xe2, v246
	s_nop 0
	v_cndmask_b32_e32 v66, v248, v98, vcc
	v_cmp_le_i32_e32 vcc, v14, v251
	v_or_b32_e32 v14, 0xc3, v246
	s_nop 0
	v_cndmask_b32_e32 v50, v248, v50, vcc
	v_cmp_le_i32_e32 vcc, v14, v251
	v_or_b32_e32 v14, 0xe3, v246
	s_nop 0
	v_cndmask_b32_e32 v67, v248, v99, vcc
	v_cmp_le_i32_e32 vcc, v14, v251
	v_or_b32_e32 v14, 0xc8, v246
	s_nop 0
	v_cndmask_b32_e32 v51, v248, v51, vcc
	v_cmp_le_i32_e32 vcc, v14, v251
	v_or_b32_e32 v14, 0xe8, v246
	s_nop 0
	v_cndmask_b32_e32 v68, v248, v100, vcc
	v_cmp_le_i32_e32 vcc, v14, v251
	v_or_b32_e32 v14, 0xc9, v246
	s_nop 0
	v_cndmask_b32_e32 v52, v248, v52, vcc
	v_cmp_le_i32_e32 vcc, v14, v251
	v_or_b32_e32 v14, 0xe9, v246
	s_nop 0
	v_cndmask_b32_e32 v69, v248, v101, vcc
	v_cmp_le_i32_e32 vcc, v14, v251
	v_or_b32_e32 v14, 0xca, v246
	s_nop 0
	v_cndmask_b32_e32 v53, v248, v53, vcc
	v_cmp_le_i32_e32 vcc, v14, v251
	v_or_b32_e32 v14, 0xea, v246
	s_nop 0
	v_cndmask_b32_e32 v70, v248, v102, vcc
	v_cmp_le_i32_e32 vcc, v14, v251
	v_or_b32_e32 v14, 0xcb, v246
	s_nop 0
	v_cndmask_b32_e32 v54, v248, v54, vcc
	v_cmp_le_i32_e32 vcc, v14, v251
	v_or_b32_e32 v14, 0xeb, v246
	s_nop 0
	v_cndmask_b32_e32 v71, v248, v103, vcc
	v_cmp_le_i32_e32 vcc, v14, v251
	v_or_b32_e32 v14, 0xd0, v246
	s_nop 0
	v_cndmask_b32_e32 v55, v248, v55, vcc
	v_cmp_le_i32_e32 vcc, v14, v251
	v_or_b32_e32 v14, 0xf0, v246
	s_nop 0
	v_cndmask_b32_e32 v72, v248, v104, vcc
	v_cmp_le_i32_e32 vcc, v14, v251
	v_or_b32_e32 v14, 0xd1, v246
	s_nop 0
	v_cndmask_b32_e32 v56, v248, v56, vcc
	v_cmp_le_i32_e32 vcc, v14, v251
	v_or_b32_e32 v14, 0xf1, v246
	s_nop 0
	v_cndmask_b32_e32 v73, v248, v105, vcc
	v_cmp_le_i32_e32 vcc, v14, v251
	v_or_b32_e32 v14, 0xd2, v246
	s_nop 0
	v_cndmask_b32_e32 v57, v248, v57, vcc
	v_cmp_le_i32_e32 vcc, v14, v251
	v_or_b32_e32 v14, 0xf2, v246
	s_nop 0
	v_cndmask_b32_e32 v74, v248, v106, vcc
	v_cmp_le_i32_e32 vcc, v14, v251
	v_or_b32_e32 v14, 0xd3, v246
	s_nop 0
	v_cndmask_b32_e32 v58, v248, v58, vcc
	v_cmp_le_i32_e32 vcc, v14, v251
	v_or_b32_e32 v14, 0xf3, v246
	s_nop 0
	v_cndmask_b32_e32 v75, v248, v107, vcc
	v_cmp_le_i32_e32 vcc, v14, v251
	v_or_b32_e32 v14, 0xd8, v246
	s_nop 0
	v_cndmask_b32_e32 v59, v248, v59, vcc
	v_cmp_le_i32_e32 vcc, v14, v251
	v_or_b32_e32 v14, 0xf8, v246
	s_nop 0
	v_cndmask_b32_e32 v76, v248, v108, vcc
	v_cmp_le_i32_e32 vcc, v14, v251
	v_or_b32_e32 v14, 0xd9, v246
	s_nop 0
	v_cndmask_b32_e32 v60, v248, v60, vcc
	v_cmp_le_i32_e32 vcc, v14, v251
	v_or_b32_e32 v14, 0xf9, v246
	s_nop 0
	v_cndmask_b32_e32 v77, v248, v109, vcc
	v_cmp_le_i32_e32 vcc, v14, v251
	v_or_b32_e32 v14, 0xda, v246
	s_nop 0
	v_cndmask_b32_e32 v61, v248, v61, vcc
	v_cmp_le_i32_e32 vcc, v14, v251
	v_or_b32_e32 v14, 0xfa, v246
	s_nop 0
	v_cndmask_b32_e32 v78, v248, v110, vcc
	v_cmp_le_i32_e32 vcc, v14, v251
	v_or_b32_e32 v14, 0xdb, v246
	s_nop 0
	v_cndmask_b32_e32 v62, v248, v62, vcc
	v_cmp_le_i32_e32 vcc, v14, v251
	v_or_b32_e32 v14, 0xfb, v246
	s_nop 0
	v_cndmask_b32_e32 v79, v248, v111, vcc
	v_cmp_le_i32_e32 vcc, v14, v251
	v_max_f32_e32 v14, v65, v65
	v_max_f32_e32 v14, v15, v14
	v_max3_f32 v15, v66, v67, v49
	v_max3_f32 v14, v14, v48, v50
	v_max3_f32 v14, v14, v51, v68
	v_max3_f32 v15, v15, v70, v71
	v_max3_f32 v14, v14, v69, v52
	v_max3_f32 v15, v15, v54, v55
	v_max3_f32 v14, v14, v53, v72
	v_max3_f32 v15, v15, v74, v75
	v_max3_f32 v14, v14, v73, v56
	v_max3_f32 v15, v15, v58, v59
	v_cndmask_b32_e32 v63, v248, v63, vcc
	v_max3_f32 v14, v14, v57, v76
	v_max3_f32 v15, v15, v78, v79
	v_max3_f32 v14, v14, v77, v60
	v_max3_f32 v15, v15, v62, v63
	v_max3_f32 v14, v14, v61, v15
	v_mov_b32_e32 v15, v14
	s_nop 1
	v_permlane32_swap_b32_e32 v14, v15
	v_max_f32_e32 v15, v15, v15
	v_max_f32_e32 v14, v14, v14
	v_max_f32_e32 v14, v14, v15
	v_cmp_lt_f32_e32 vcc, s91, v14
	s_cmp_lg_u64 vcc, 0
	s_cselect_b64 s[2:3], -1, 0
	s_cbranch_vccnz .LBB0_313
.LBB0_259:
	v_add_u32_e32 v160, s45, v254
	s_waitcnt lgkmcnt(14)
	v_mfma_f32_32x32x16_bf16 v[32:47], v[156:159], v[6:9], v[32:47]
	v_exp_f32_e32 v64, v64
	v_exp_f32_e32 v65, v65
	ds_read_b64_tr_b16 v[6:7], v160 offset:24576
	ds_read_b64_tr_b16 v[8:9], v160 offset:25088
	s_waitcnt lgkmcnt(14)
	v_mfma_f32_32x32x16_bf16 v[16:31], v[156:159], v[2:5], v[16:31]
	v_exp_f32_e32 v66, v66
	v_exp_f32_e32 v67, v67
	ds_read_b64_tr_b16 v[2:3], v160 offset:28672
	ds_read_b64_tr_b16 v[4:5], v160 offset:29184
	s_waitcnt lgkmcnt(14)
	v_mfma_f32_32x32x16_bf16 v[32:47], v[152:155], v[10:13], v[32:47]
	v_exp_f32_e32 v68, v68
	v_exp_f32_e32 v69, v69
	ds_read_b64_tr_b16 v[10:11], v160 offset:25600
	ds_read_b64_tr_b16 v[12:13], v160 offset:26112
	s_waitcnt lgkmcnt(14)
	v_mfma_f32_32x32x16_bf16 v[16:31], v[152:155], v[112:115], v[16:31]
	v_exp_f32_e32 v70, v70
	v_exp_f32_e32 v71, v71
	ds_read_b64_tr_b16 v[112:113], v160 offset:29696
	ds_read_b64_tr_b16 v[114:115], v160 offset:30208
	s_waitcnt lgkmcnt(14)
	v_mfma_f32_32x32x16_bf16 v[32:47], v[144:147], v[116:119], v[32:47]
	v_exp_f32_e32 v72, v72
	v_exp_f32_e32 v73, v73
	ds_read_b64_tr_b16 v[116:117], v160 offset:26624
	ds_read_b64_tr_b16 v[118:119], v160 offset:27136
	s_waitcnt lgkmcnt(14)
	v_mfma_f32_32x32x16_bf16 v[16:31], v[144:147], v[120:123], v[16:31]
	v_exp_f32_e32 v74, v74
	v_exp_f32_e32 v75, v75
	ds_read_b64_tr_b16 v[120:121], v160 offset:30720
	ds_read_b64_tr_b16 v[122:123], v160 offset:31232
	s_waitcnt lgkmcnt(14)
	v_mfma_f32_32x32x16_bf16 v[32:47], v[136:139], v[124:127], v[32:47]
	v_exp_f32_e32 v76, v76
	v_exp_f32_e32 v77, v77
	ds_read_b64_tr_b16 v[124:125], v160 offset:27648
	ds_read_b64_tr_b16 v[126:127], v160 offset:28160
	s_waitcnt lgkmcnt(14)
	v_mfma_f32_32x32x16_bf16 v[16:31], v[136:139], v[132:135], v[16:31]
	v_exp_f32_e32 v78, v78
	v_exp_f32_e32 v79, v79
	ds_read_b64_tr_b16 v[132:133], v160 offset:31744
	ds_read_b64_tr_b16 v[134:135], v160 offset:32256
	s_waitcnt lgkmcnt(14)
	v_mfma_f32_32x32x16_bf16 v[226:241], v[156:159], v[6:9], v[226:241]
	v_exp_f32_e32 v48, v48
	v_exp_f32_e32 v49, v49
	s_waitcnt lgkmcnt(12)
	v_mfma_f32_32x32x16_bf16 v[208:223], v[156:159], v[2:5], v[208:223]
	v_exp_f32_e32 v50, v50
	v_exp_f32_e32 v51, v51
	s_waitcnt lgkmcnt(10)
	v_mfma_f32_32x32x16_bf16 v[226:241], v[152:155], v[10:13], v[226:241]
	v_exp_f32_e32 v52, v52
	v_exp_f32_e32 v53, v53
	s_waitcnt lgkmcnt(8)
	v_mfma_f32_32x32x16_bf16 v[208:223], v[152:155], v[112:115], v[208:223]
	v_exp_f32_e32 v54, v54
	v_exp_f32_e32 v55, v55
	s_waitcnt lgkmcnt(6)
	v_mfma_f32_32x32x16_bf16 v[226:241], v[144:147], v[116:119], v[226:241]
	v_exp_f32_e32 v56, v56
	v_exp_f32_e32 v57, v57
	s_waitcnt lgkmcnt(4)
	v_mfma_f32_32x32x16_bf16 v[208:223], v[144:147], v[120:123], v[208:223]
	v_exp_f32_e32 v58, v58
	v_exp_f32_e32 v59, v59
	s_waitcnt lgkmcnt(2)
	v_mfma_f32_32x32x16_bf16 v[226:241], v[136:139], v[124:127], v[226:241]
	v_exp_f32_e32 v60, v60
	v_exp_f32_e32 v61, v61
	s_waitcnt lgkmcnt(0)
	v_mfma_f32_32x32x16_bf16 v[208:223], v[136:139], v[132:135], v[208:223]
	v_exp_f32_e32 v62, v62
	v_exp_f32_e32 v63, v63
	s_andn2_b64 vcc, exec, s[2:3]
	v_lshl_add_u32 v2, v246, 2, s37
	s_cbranch_vccnz .LBB0_261
	s_waitcnt lgkmcnt(0)
	ds_read_b128 v[4:7], v2 offset:49248
	ds_read_b128 v[8:11], v2 offset:49216
	ds_read_b128 v[12:15], v2 offset:49184
	ds_read_b128 v[80:83], v2 offset:49152
	s_waitcnt lgkmcnt(3)
	v_pk_mul_f32 v[46:47], v[46:47], v[6:7]
	s_waitcnt lgkmcnt(2)
	v_pk_mul_f32 v[42:43], v[42:43], v[10:11]
	s_waitcnt lgkmcnt(1)
	v_pk_mul_f32 v[38:39], v[38:39], v[14:15]
	s_waitcnt lgkmcnt(0)
	v_pk_mul_f32 v[34:35], v[34:35], v[82:83]
	v_pk_mul_f32 v[44:45], v[44:45], v[4:5]
	v_pk_mul_f32 v[40:41], v[40:41], v[8:9]
	v_pk_mul_f32 v[36:37], v[36:37], v[12:13]
	v_pk_mul_f32 v[32:33], v[32:33], v[80:81]
	v_pk_mul_f32 v[30:31], v[30:31], v[6:7]
	v_pk_mul_f32 v[26:27], v[26:27], v[10:11]
	v_pk_mul_f32 v[22:23], v[22:23], v[14:15]
	v_pk_mul_f32 v[18:19], v[18:19], v[82:83]
	v_pk_mul_f32 v[28:29], v[28:29], v[4:5]
	v_pk_mul_f32 v[24:25], v[24:25], v[8:9]
	v_pk_mul_f32 v[20:21], v[20:21], v[12:13]
	v_pk_mul_f32 v[16:17], v[16:17], v[80:81]
	v_pk_mul_f32 v[240:241], v[240:241], v[6:7]
	v_pk_mul_f32 v[236:237], v[236:237], v[10:11]
	v_pk_mul_f32 v[232:233], v[232:233], v[14:15]
	v_pk_mul_f32 v[228:229], v[228:229], v[82:83]
	v_pk_mul_f32 v[238:239], v[238:239], v[4:5]
	v_pk_mul_f32 v[234:235], v[234:235], v[8:9]
	v_pk_mul_f32 v[230:231], v[230:231], v[12:13]
	v_pk_mul_f32 v[226:227], v[226:227], v[80:81]
	v_pk_mul_f32 v[222:223], v[222:223], v[6:7]
	v_pk_mul_f32 v[218:219], v[218:219], v[10:11]
	v_pk_mul_f32 v[214:215], v[214:215], v[14:15]
	v_pk_mul_f32 v[210:211], v[210:211], v[82:83]
	v_pk_mul_f32 v[220:221], v[220:221], v[4:5]
	v_pk_mul_f32 v[216:217], v[216:217], v[8:9]
	v_pk_mul_f32 v[212:213], v[212:213], v[12:13]
	v_pk_mul_f32 v[208:209], v[208:209], v[80:81]
; #define SBAR() __builtin_amdgcn_sched_barrier(0)
;   #define RESC() do{ if(resc){ asm volatile("s_waitcnt lgkmcnt(0)":::"memory"); \
;       _Pragma("unroll") for(int d_=0;d_<2;++d_) _Pragma("unroll") for(int r=0;r<16;++r)o[d_][r]*=wsf[crow(r,hi)]; } }while(0)
;   #define PKW(P,B) cvtpk_s(P[B],P[B+1])
; __device__ __forceinline__ void pv(f32x16*o,int vb,bf16x8 pa0,bf16x8 pa1,bf16x8 pa2,bf16x8 pa3){
;   #pragma unroll
;   for(int d0=0;d0<2;++d0){s16x4 lo[4],hi[4];
;     #pragma unroll
;     for(int ks=0;ks<4;++ks){
;       asm volatile("ds_read_b64_tr_b16 %0,%1 offset:%c2":"=&v"(lo[ks]):"v"(vb),"i"(d0*4096+ks*1024):"memory");
;       asm volatile("ds_read_b64_tr_b16 %0,%1 offset:%c2":"=&v"(hi[ks]):"v"(vb),"i"(d0*4096+ks*1024+512):"memory");}
;     asm volatile("s_waitcnt lgkmcnt(0)":::"memory");SBAR();
;     ...
;     o[d0]=__builtin_amdgcn_mfma_f32_32x32x16_bf16(pa0,PK(0),o[d0],0,0,0);
;     o[d0]=__builtin_amdgcn_mfma_f32_32x32x16_bf16(pa1,PK(1),o[d0],0,0,0);
;     o[d0]=__builtin_amdgcn_mfma_f32_32x32x16_bf16(pa2,PK(2),o[d0],0,0,0);
;     o[d0]=__builtin_amdgcn_mfma_f32_32x32x16_bf16(pa3,PK(3),o[d0],0,0,0);
;     ...
;   }
; }
; template<int THRL> __device__ __forceinline__ void attn_unit(int b,int colq,int colk,int colv,int colo,int qb,const bf16*Q,const bf16*__restrict__ K,const bf16*__restrict__ V,bf16*O,char*shm,const int tid_in){
;     ...
;   STEP(pB0,pB1,pA0,pA1,NT-1,false,false,false); RESC();
;   { float sacc=pB0[0]+pB0[1]; _Pragma("unroll") for(int r=2;r<16;++r)sacc+=pB0[r]; _Pragma("unroll") for(int r=0;r<16;++r)sacc+=pB1[r]; l_reg+=sacc;
;     pw0=(u32x4){PKW(pB0,0),PKW(pB0,2),PKW(pB0,4),PKW(pB0,6)};pw1=(u32x4){PKW(pB0,8),PKW(pB0,10),PKW(pB0,12),PKW(pB0,14)};pw2=(u32x4){PKW(pB1,0),PKW(pB1,2),PKW(pB1,4),PKW(pB1,6)};pw3=(u32x4){PKW(pB1,8),PKW(pB1,10),PKW(pB1,12),PKW(pB1,14)};
;     SBAR(); pv(o,vb0+sl_cur,PAF(0),PAF(1),PAF(2),PAF(3)); }
;     ...
;   {auto rr=__builtin_amdgcn_permlane32_swap(__float_as_uint(l_reg),__float_as_uint(l_reg),false,false);l_reg=__uint_as_float(rr[0])+__uint_as_float(rr[1]);}
;   if(hi==0)wsf[32+r32]=l_reg;asm volatile("s_waitcnt lgkmcnt(0)":::"memory");
.LBB0_261:
	v_add_f32_e32 v4, v64, v65
	v_add_f32_e32 v4, v66, v4
	v_add_f32_e32 v4, v67, v4
	v_add_f32_e32 v4, v68, v4
	v_add_f32_e32 v4, v69, v4
	v_add_f32_e32 v4, v70, v4
	v_add_f32_e32 v4, v71, v4
	v_add_f32_e32 v4, v72, v4
	v_add_f32_e32 v4, v73, v4
	v_add_f32_e32 v4, v74, v4
	v_add_f32_e32 v4, v75, v4
	v_add_f32_e32 v4, v76, v4
	v_add_f32_e32 v4, v77, v4
	v_add_f32_e32 v4, v78, v4
	v_add_f32_e32 v4, v79, v4
	v_add_f32_e32 v4, v48, v4
	v_add_f32_e32 v4, v49, v4
	v_add_f32_e32 v4, v50, v4
	v_add_f32_e32 v4, v51, v4
	v_add_f32_e32 v4, v52, v4
	v_add_f32_e32 v4, v53, v4
	v_add_f32_e32 v4, v54, v4
	v_add_f32_e32 v4, v55, v4
	v_add_f32_e32 v4, v56, v4
	v_add_f32_e32 v4, v57, v4
	v_add_f32_e32 v4, v58, v4
	v_add_f32_e32 v4, v59, v4
	v_add_f32_e32 v4, v60, v4
	s_cmp_lg_u32 0, -1
	v_add_f32_e32 v4, v61, v4
	s_cselect_b32 s2, 0, 0
	v_add_f32_e32 v4, v62, v4
	s_addk_i32 s2, 0x6000
	v_add_f32_e32 v4, v63, v4
	v_add3_u32 v3, v247, s2, v244
	v_add_f32_e32 v0, v0, v4
	v_cvt_pk_bf16_f32 v4, v64, v65
	v_cvt_pk_bf16_f32 v5, v66, v67
	v_cvt_pk_bf16_f32 v6, v68, v69
	v_cvt_pk_bf16_f32 v7, v70, v71
	v_cvt_pk_bf16_f32 v8, v72, v73
	v_cvt_pk_bf16_f32 v9, v74, v75
	v_cvt_pk_bf16_f32 v10, v76, v77
	v_cvt_pk_bf16_f32 v11, v78, v79
	v_cvt_pk_bf16_f32 v12, v48, v49
	v_cvt_pk_bf16_f32 v13, v50, v51
	v_cvt_pk_bf16_f32 v14, v52, v53
	v_cvt_pk_bf16_f32 v15, v54, v55
	v_cvt_pk_bf16_f32 v48, v56, v57
	v_cvt_pk_bf16_f32 v49, v58, v59
	v_cvt_pk_bf16_f32 v50, v60, v61
	v_cvt_pk_bf16_f32 v51, v62, v63
	v_add3_u32 v3, v3, v245, s41
	v_add_u32_e32 v176, 0xe800, v3
	ds_read_b64_tr_b16 v[52:53],v3 offset:0
	ds_read_b64_tr_b16 v[54:55],v3 offset:512
	ds_read_b64_tr_b16 v[56:57],v3 offset:1024
	ds_read_b64_tr_b16 v[58:59],v3 offset:1536
	ds_read_b64_tr_b16 v[60:61],v3 offset:2048
	ds_read_b64_tr_b16 v[62:63],v3 offset:2560
	ds_read_b64_tr_b16 v[64:65],v3 offset:3072
	ds_read_b64_tr_b16 v[66:67],v3 offset:3584
	s_waitcnt lgkmcnt(0)
	s_nop 0
	v_mfma_f32_32x32x16_bf16 v[32:47], v[4:7], v[52:55], v[32:47]
	ds_read_b64_tr_b16 v[52:53],v3 offset:4096
	ds_read_b64_tr_b16 v[54:55],v3 offset:4608
	v_mfma_f32_32x32x16_bf16 v[32:47], v[8:11], v[56:59], v[32:47]
	ds_read_b64_tr_b16 v[56:57],v3 offset:5120
	ds_read_b64_tr_b16 v[58:59],v3 offset:5632
	v_mfma_f32_32x32x16_bf16 v[32:47], v[12:15], v[60:63], v[32:47]
	ds_read_b64_tr_b16 v[60:61],v3 offset:6144
	ds_read_b64_tr_b16 v[62:63],v3 offset:6656
	v_mfma_f32_32x32x16_bf16 v[32:47], v[48:51], v[64:67], v[32:47]
	ds_read_b64_tr_b16 v[64:65],v3 offset:7168
	ds_read_b64_tr_b16 v[66:67],v3 offset:7680
	s_waitcnt lgkmcnt(0)
	v_mfma_f32_32x32x16_bf16 v[16:31], v[4:7], v[52:55], v[16:31]
	v_mov_b32_e32 v3, v0
	s_nop 1
	v_permlane32_swap_b32_e32 v0, v3
	v_cmp_gt_u32_e32 vcc, 32, v206
	v_mfma_f32_32x32x16_bf16 v[16:31], v[8:11], v[56:59], v[16:31]
	v_mfma_f32_32x32x16_bf16 v[16:31], v[12:15], v[60:63], v[16:31]
	v_mfma_f32_32x32x16_bf16 v[16:31], v[48:51], v[64:67], v[16:31]
	ds_read_b64_tr_b16 v[160:161], v176 offset:0
	ds_read_b64_tr_b16 v[162:163], v176 offset:512
	ds_read_b64_tr_b16 v[164:165], v176 offset:1024
	ds_read_b64_tr_b16 v[166:167], v176 offset:1536
	ds_read_b64_tr_b16 v[168:169], v176 offset:2048
	ds_read_b64_tr_b16 v[170:171], v176 offset:2560
	ds_read_b64_tr_b16 v[172:173], v176 offset:3072
	ds_read_b64_tr_b16 v[174:175], v176 offset:3584
	s_waitcnt lgkmcnt(0)
	v_mfma_f32_32x32x16_bf16 v[226:241], v[4:7], v[160:163], v[226:241]
	v_mfma_f32_32x32x16_bf16 v[226:241], v[8:11], v[164:167], v[226:241]
	v_mfma_f32_32x32x16_bf16 v[226:241], v[12:15], v[168:171], v[226:241]
	v_mfma_f32_32x32x16_bf16 v[226:241], v[48:51], v[172:175], v[226:241]
	ds_read_b64_tr_b16 v[180:181], v176 offset:4096
	ds_read_b64_tr_b16 v[182:183], v176 offset:4608
	ds_read_b64_tr_b16 v[184:185], v176 offset:5120
	ds_read_b64_tr_b16 v[186:187], v176 offset:5632
	ds_read_b64_tr_b16 v[188:189], v176 offset:6144
	ds_read_b64_tr_b16 v[190:191], v176 offset:6656
	ds_read_b64_tr_b16 v[192:193], v176 offset:7168
	ds_read_b64_tr_b16 v[194:195], v176 offset:7680
	s_waitcnt lgkmcnt(0)
	v_mfma_f32_32x32x16_bf16 v[208:223], v[4:7], v[180:183], v[208:223]
	v_mfma_f32_32x32x16_bf16 v[208:223], v[8:11], v[184:187], v[208:223]
	v_mfma_f32_32x32x16_bf16 v[208:223], v[12:15], v[188:191], v[208:223]
	v_mfma_f32_32x32x16_bf16 v[208:223], v[48:51], v[192:195], v[208:223]
	s_and_saveexec_b64 s[2:3], vcc
	s_cbranch_execz .LBB0_237
	v_add_f32_e32 v0, v0, v3
	ds_write_b32 v250, v0 offset:49280
	s_branch .LBB0_237

.LBB0_264:
	s_lshl_b32 s4, s16, 6
	s_addk_i32 s4, 0x7b
	v_add_u32_e32 v0, s4, v246
	s_lshl_b32 s4, s18, 2
	s_sub_i32 s43, 0, s4
	v_mad_u64_u32 v[14:15], s[4:5], s16, v249, v[198:199]
	v_mad_u64_u32 v[2:3], s[4:5], s16, v249, v[196:197]
	s_mov_b64 s[4:5], 0x1c0000
	v_cmp_gt_u32_e64 s[2:3], 32, v206
	v_subrev_u32_e32 v0, s19, v0
	s_add_i32 s21, s16, 2
	v_lshl_add_u64 v[204:205], v[2:3], 0, s[4:5]
.LBB0_265:
	v_add_u32_e32 v196, s20, v254
	s_add_i32 s45, s20, 0xe800
	ds_read_b64_tr_b16 v[192:193], v196 offset:24576
	ds_read_b64_tr_b16 v[194:195], v196 offset:25088
	s_waitcnt lgkmcnt(9)
	v_mfma_f32_32x32x16_bf16 v[112:127], v[188:191], v[148:151], v[48:63]
	v_add_f32_e32 v2, v80, v81
	v_add_f32_e32 v2, v82, v2
	v_add_f32_e32 v2, v83, v2
	v_add_f32_e32 v2, v84, v2
	v_add_f32_e32 v2, v85, v2
	v_cvt_pk_bf16_f32 v156, v80, v81
	v_cvt_pk_bf16_f32 v157, v82, v83
	ds_read_b64_tr_b16 v[80:81], v196 offset:28672
	ds_read_b64_tr_b16 v[82:83], v196 offset:29184
	s_waitcnt lgkmcnt(10)
	v_mfma_f32_32x32x16_bf16 v[96:111], v[184:187], v[148:151], v[48:63]
	v_add_f32_e32 v2, v86, v2
	v_add_f32_e32 v2, v87, v2
	v_add_f32_e32 v2, v88, v2
	v_add_f32_e32 v6, v89, v2
	v_cvt_pk_bf16_f32 v158, v84, v85
	v_cvt_pk_bf16_f32 v159, v86, v87
	ds_read_b64_tr_b16 v[2:3], v196 offset:25600
	ds_read_b64_tr_b16 v[4:5], v196 offset:26112
	s_waitcnt lgkmcnt(11)
	v_mfma_f32_32x32x16_bf16 v[112:127], v[180:183], v[140:143], v[112:127]
	v_add_f32_e32 v6, v90, v6
	v_add_f32_e32 v6, v91, v6
	v_add_f32_e32 v6, v92, v6
	v_add_f32_e32 v10, v93, v6
	v_cvt_pk_bf16_f32 v152, v88, v89
	v_cvt_pk_bf16_f32 v153, v90, v91
	ds_read_b64_tr_b16 v[6:7], v196 offset:29696
	ds_read_b64_tr_b16 v[8:9], v196 offset:30208
	s_waitcnt lgkmcnt(12)
	v_mfma_f32_32x32x16_bf16 v[96:111], v[176:179], v[140:143], v[96:111]
	v_add_f32_e32 v10, v94, v10
	v_add_f32_e32 v10, v95, v10
	v_add_f32_e32 v10, v64, v10
	v_add_f32_e32 v84, v65, v10
	v_cvt_pk_bf16_f32 v154, v92, v93
	v_cvt_pk_bf16_f32 v155, v94, v95
	ds_read_b64_tr_b16 v[10:11], v196 offset:26624
	ds_read_b64_tr_b16 v[12:13], v196 offset:27136
	s_waitcnt lgkmcnt(13)
	v_mfma_f32_32x32x16_bf16 v[112:127], v[172:175], v[132:135], v[112:127]
	v_add_f32_e32 v84, v66, v84
	v_add_f32_e32 v84, v67, v84
	v_add_f32_e32 v84, v68, v84
	v_add_f32_e32 v84, v69, v84
	v_cvt_pk_bf16_f32 v144, v64, v65
	v_cvt_pk_bf16_f32 v145, v66, v67
	ds_read_b64_tr_b16 v[64:65], v196 offset:30720
	ds_read_b64_tr_b16 v[66:67], v196 offset:31232
	s_waitcnt lgkmcnt(14)
	v_mfma_f32_32x32x16_bf16 v[96:111], v[168:171], v[132:135], v[96:111]
	v_add_f32_e32 v84, v70, v84
	v_add_f32_e32 v84, v71, v84
	v_add_f32_e32 v84, v72, v84
	v_add_f32_e32 v84, v73, v84
	v_cvt_pk_bf16_f32 v146, v68, v69
	v_cvt_pk_bf16_f32 v147, v70, v71
	ds_read_b64_tr_b16 v[68:69], v196 offset:27648
	ds_read_b64_tr_b16 v[70:71], v196 offset:28160
	s_waitcnt lgkmcnt(14)
	v_mfma_f32_32x32x16_bf16 v[112:127], v[164:167], v[128:131], v[112:127]
	v_add_f32_e32 v84, v74, v84
	v_add_f32_e32 v84, v75, v84
	v_add_f32_e32 v84, v76, v84
	v_add_f32_e32 v84, v77, v84
	v_cvt_pk_bf16_f32 v136, v72, v73
	v_cvt_pk_bf16_f32 v137, v74, v75
	ds_read_b64_tr_b16 v[72:73], v196 offset:31744
	ds_read_b64_tr_b16 v[74:75], v196 offset:32256
	v_mfma_f32_32x32x16_bf16 v[96:111], v[160:163], v[128:131], v[96:111]
	v_add_f32_e32 v84, v78, v84
	v_add_f32_e32 v84, v79, v84
	v_add_f32_e32 v84, 0, v84
	v_cvt_pk_bf16_f32 v138, v76, v77
	v_cvt_pk_bf16_f32 v139, v78, v79
	s_add_i32 s4, s21, 1
	s_cmp_ge_u32 s4, s40
	s_cselect_b64 s[16:17], -1, 0
	s_and_b64 vcc, exec, s[16:17]
	s_cbranch_vccnz .LBB0_267
	v_lshl_add_u64 v[76:77], v[204:205], 0, s[86:87]
	s_add_i32 s4, s41, s38
	s_mov_b32 s5, m0
	s_mov_b32 m0, s4
	s_nop 0
	global_load_lds_dwordx4 v[76:77], off
	s_mov_b32 m0, s5
; __device__ __forceinline__ void cmask(f32x16&p0,f32x16&p1,int jb,int qrel,int hi){
;   const float NEG=-INFINITY; int kb=64*jb+4*hi;
;   #pragma unroll
;   for(int r=0;r<16;++r){int kv=kb+(r&3)+8*(r>>2); if(kv>qrel)p0[r]=NEG; if(kv+32>qrel)p1[r]=NEG;}
; }
.LBB0_267:
	s_add_i32 s4, s42, s39
	s_mov_b32 s5, m0
	s_mov_b32 m0, s4
	s_nop 0
	global_load_lds_dwordx4 v[14:15], off
	s_mov_b32 m0, s5
	s_add_i32 s46, s4, 0xe780
	s_mov_b32 s47, m0
	s_mov_b32 m0, s46
	s_nop 0
	global_load_lds_dwordx4 v[14:15], off offset:128
	s_mov_b32 m0, s47
	s_add_i32 s20, s43, s21
	s_add_i32 s4, s20, -2
	s_cmp_lt_i32 s4, 0
	s_cbranch_scc1 .LBB0_269
	v_add_u32_e32 v77, 0xffffffa5, v0
	v_add_u32_e32 v76, 0xffffff85, v0
	v_cmp_le_i32_e32 vcc, v77, v251
	s_nop 1
	v_cndmask_b32_e32 v96, v248, v96, vcc
	v_cmp_lt_i32_e32 vcc, v76, v251
	s_nop 1
	v_cndmask_b32_e32 v113, v248, v113, vcc
	v_cmp_le_i32_e32 vcc, v76, v251
	v_add_u32_e32 v76, 0xffffffa6, v0
	s_nop 0
	v_cndmask_b32_e32 v112, v248, v112, vcc
	v_cmp_le_i32_e32 vcc, v76, v251
	v_add_u32_e32 v76, 0xffffff87, v0
	s_nop 0
	v_cndmask_b32_e32 v97, v248, v97, vcc
	v_cmp_le_i32_e32 vcc, v76, v251
	v_add_u32_e32 v76, 0xffffffa7, v0
	s_nop 0
	v_cndmask_b32_e32 v114, v248, v114, vcc
	v_cmp_le_i32_e32 vcc, v76, v251
	v_add_u32_e32 v76, 0xffffff88, v0
	s_nop 0
	v_cndmask_b32_e32 v98, v248, v98, vcc
	v_cmp_le_i32_e32 vcc, v76, v251
	v_add_u32_e32 v76, 0xffffffa8, v0
	s_nop 0
	v_cndmask_b32_e32 v115, v248, v115, vcc
	v_cmp_le_i32_e32 vcc, v76, v251
	v_add_u32_e32 v76, 0xffffff8d, v0
	s_nop 0
	v_cndmask_b32_e32 v99, v248, v99, vcc
	v_cmp_le_i32_e32 vcc, v76, v251
	v_add_u32_e32 v76, 0xffffffad, v0
	s_nop 0
	v_cndmask_b32_e32 v116, v248, v116, vcc
	v_cmp_le_i32_e32 vcc, v76, v251
	v_add_u32_e32 v76, 0xffffff8e, v0
	s_nop 0
	v_cndmask_b32_e32 v100, v248, v100, vcc
	v_cmp_le_i32_e32 vcc, v76, v251
	v_add_u32_e32 v76, 0xffffffae, v0
	s_nop 0
	v_cndmask_b32_e32 v117, v248, v117, vcc
	v_cmp_le_i32_e32 vcc, v76, v251
	v_add_u32_e32 v76, 0xffffff8f, v0
	s_nop 0
	v_cndmask_b32_e32 v101, v248, v101, vcc
	v_cmp_le_i32_e32 vcc, v76, v251
	v_add_u32_e32 v76, 0xffffffaf, v0
	s_nop 0
	v_cndmask_b32_e32 v118, v248, v118, vcc
	v_cmp_le_i32_e32 vcc, v76, v251
	v_add_u32_e32 v76, 0xffffff90, v0
	s_nop 0
	v_cndmask_b32_e32 v102, v248, v102, vcc
	v_cmp_le_i32_e32 vcc, v76, v251
	v_add_u32_e32 v76, 0xffffffb0, v0
	s_nop 0
	v_cndmask_b32_e32 v119, v248, v119, vcc
	v_cmp_le_i32_e32 vcc, v76, v251
	v_add_u32_e32 v76, 0xffffff95, v0
	s_nop 0
	v_cndmask_b32_e32 v103, v248, v103, vcc
	v_cmp_le_i32_e32 vcc, v76, v251
	v_add_u32_e32 v76, 0xffffffb5, v0
	s_nop 0
	v_cndmask_b32_e32 v120, v248, v120, vcc
	v_cmp_le_i32_e32 vcc, v76, v251
	v_add_u32_e32 v76, 0xffffff96, v0
	s_nop 0
	v_cndmask_b32_e32 v104, v248, v104, vcc
	v_cmp_le_i32_e32 vcc, v76, v251
	v_add_u32_e32 v76, 0xffffffb6, v0
	s_nop 0
	v_cndmask_b32_e32 v121, v248, v121, vcc
	v_cmp_le_i32_e32 vcc, v76, v251
	v_add_u32_e32 v76, 0xffffff97, v0
	s_nop 0
	v_cndmask_b32_e32 v105, v248, v105, vcc
	v_cmp_le_i32_e32 vcc, v76, v251
	v_add_u32_e32 v76, 0xffffffb7, v0
	s_nop 0
	v_cndmask_b32_e32 v122, v248, v122, vcc
	v_cmp_le_i32_e32 vcc, v76, v251
	v_add_u32_e32 v76, 0xffffff98, v0
	s_nop 0
	v_cndmask_b32_e32 v106, v248, v106, vcc
	v_cmp_le_i32_e32 vcc, v76, v251
	v_add_u32_e32 v76, 0xffffffb8, v0
	s_nop 0
	v_cndmask_b32_e32 v123, v248, v123, vcc
	v_cmp_le_i32_e32 vcc, v76, v251
	v_add_u32_e32 v76, 0xffffff9d, v0
	s_nop 0
	v_cndmask_b32_e32 v107, v248, v107, vcc
	v_cmp_le_i32_e32 vcc, v76, v251
	v_add_u32_e32 v76, 0xffffffbd, v0
	s_nop 0
	v_cndmask_b32_e32 v124, v248, v124, vcc
	v_cmp_le_i32_e32 vcc, v76, v251
	v_add_u32_e32 v76, 0xffffff9e, v0
	s_nop 0
	v_cndmask_b32_e32 v108, v248, v108, vcc
	v_cmp_le_i32_e32 vcc, v76, v251
	v_add_u32_e32 v76, 0xffffffbe, v0
	s_nop 0
	v_cndmask_b32_e32 v125, v248, v125, vcc
	v_cmp_le_i32_e32 vcc, v76, v251
	v_add_u32_e32 v76, 0xffffff9f, v0
	s_nop 0
	v_cndmask_b32_e32 v109, v248, v109, vcc
	v_cmp_le_i32_e32 vcc, v76, v251
	v_add_u32_e32 v76, 0xffffffbf, v0
	s_nop 0
	v_cndmask_b32_e32 v126, v248, v126, vcc
	v_cmp_le_i32_e32 vcc, v76, v251
	v_add_u32_e32 v76, 0xffffffa0, v0
	s_nop 0
	v_cndmask_b32_e32 v110, v248, v110, vcc
	v_cmp_le_i32_e32 vcc, v76, v251
	v_subrev_u32_e32 v76, 64, v0
	s_nop 0
	v_cndmask_b32_e32 v127, v248, v127, vcc
	v_cmp_le_i32_e32 vcc, v76, v251
	s_nop 1
	v_cndmask_b32_e32 v111, v248, v111, vcc

.LBB0_270:
	v_add_u32_e32 v76, s45, v254
	s_waitcnt lgkmcnt(14)
	v_mfma_f32_32x32x16_bf16 v[32:47], v[156:159], v[192:195], v[32:47]
	v_exp_f32_e32 v112, v112
	v_exp_f32_e32 v113, v113
	ds_read_b64_tr_b16 v[192:193], v76 offset:24576
	ds_read_b64_tr_b16 v[194:195], v76 offset:25088
	s_waitcnt lgkmcnt(14)
	v_mfma_f32_32x32x16_bf16 v[16:31], v[156:159], v[80:83], v[16:31]
	v_exp_f32_e32 v114, v114
	v_exp_f32_e32 v115, v115
	ds_read_b64_tr_b16 v[80:81], v76 offset:28672
	ds_read_b64_tr_b16 v[82:83], v76 offset:29184
	s_waitcnt lgkmcnt(14)
	v_mfma_f32_32x32x16_bf16 v[32:47], v[152:155], v[2:5], v[32:47]
	v_exp_f32_e32 v116, v116
	v_exp_f32_e32 v117, v117
	ds_read_b64_tr_b16 v[2:3], v76 offset:25600
	ds_read_b64_tr_b16 v[4:5], v76 offset:26112
	s_waitcnt lgkmcnt(14)
	v_mfma_f32_32x32x16_bf16 v[16:31], v[152:155], v[6:9], v[16:31]
	v_exp_f32_e32 v118, v118
	v_exp_f32_e32 v119, v119
	ds_read_b64_tr_b16 v[6:7], v76 offset:29696
	ds_read_b64_tr_b16 v[8:9], v76 offset:30208
	s_waitcnt lgkmcnt(14)
	v_mfma_f32_32x32x16_bf16 v[32:47], v[144:147], v[10:13], v[32:47]
	v_exp_f32_e32 v120, v120
	v_exp_f32_e32 v121, v121
	ds_read_b64_tr_b16 v[10:11], v76 offset:26624
	ds_read_b64_tr_b16 v[12:13], v76 offset:27136
	s_waitcnt lgkmcnt(14)
	v_mfma_f32_32x32x16_bf16 v[16:31], v[144:147], v[64:67], v[16:31]
	v_exp_f32_e32 v122, v122
	v_exp_f32_e32 v123, v123
	ds_read_b64_tr_b16 v[64:65], v76 offset:30720
	ds_read_b64_tr_b16 v[66:67], v76 offset:31232
	s_waitcnt lgkmcnt(14)
	v_mfma_f32_32x32x16_bf16 v[32:47], v[136:139], v[68:71], v[32:47]
	v_exp_f32_e32 v124, v124
	v_exp_f32_e32 v125, v125
	ds_read_b64_tr_b16 v[68:69], v76 offset:27648
	ds_read_b64_tr_b16 v[70:71], v76 offset:28160
	s_waitcnt lgkmcnt(14)
	v_mfma_f32_32x32x16_bf16 v[16:31], v[136:139], v[72:75], v[16:31]
	v_exp_f32_e32 v126, v126
	v_exp_f32_e32 v127, v127
	ds_read_b64_tr_b16 v[72:73], v76 offset:31744
	ds_read_b64_tr_b16 v[74:75], v76 offset:32256
	s_waitcnt lgkmcnt(14)
	v_mfma_f32_32x32x16_bf16 v[226:241], v[156:159], v[192:195], v[226:241]
	v_exp_f32_e32 v96, v96
	v_exp_f32_e32 v97, v97
	s_waitcnt lgkmcnt(12)
	v_mfma_f32_32x32x16_bf16 v[208:223], v[156:159], v[80:83], v[208:223]
	v_exp_f32_e32 v98, v98
	v_exp_f32_e32 v99, v99
	v_add_u32_e32 v76, s42, v253
	ds_read_b128 v[188:191], v76
	ds_read_b128 v[184:187], v76 offset:512
	s_waitcnt lgkmcnt(12)
	v_mfma_f32_32x32x16_bf16 v[226:241], v[152:155], v[2:5], v[226:241]
	v_exp_f32_e32 v100, v100
	v_exp_f32_e32 v101, v101
	ds_read_b128 v[180:183], v76 offset:2048
	ds_read_b128 v[176:179], v76 offset:2560
	s_waitcnt lgkmcnt(12)
	v_mfma_f32_32x32x16_bf16 v[208:223], v[152:155], v[6:9], v[208:223]
	v_exp_f32_e32 v102, v102
	v_exp_f32_e32 v103, v103
	ds_read_b128 v[172:175], v76 offset:4096
	ds_read_b128 v[168:171], v76 offset:4608
	s_waitcnt lgkmcnt(12)
	v_mfma_f32_32x32x16_bf16 v[226:241], v[144:147], v[10:13], v[226:241]
	v_exp_f32_e32 v104, v104
	v_exp_f32_e32 v105, v105
	ds_read_b128 v[164:167], v76 offset:6144
	ds_read_b128 v[160:163], v76 offset:6656
	s_waitcnt lgkmcnt(12)
	v_mfma_f32_32x32x16_bf16 v[208:223], v[144:147], v[64:67], v[208:223]
	v_exp_f32_e32 v106, v106
	v_exp_f32_e32 v107, v107
	s_waitcnt lgkmcnt(10)
	v_mfma_f32_32x32x16_bf16 v[226:241], v[136:139], v[68:71], v[226:241]
	v_exp_f32_e32 v108, v108
	v_exp_f32_e32 v109, v109
	s_waitcnt lgkmcnt(8)
	v_mfma_f32_32x32x16_bf16 v[208:223], v[136:139], v[72:75], v[208:223]
	v_exp_f32_e32 v110, v110
	v_exp_f32_e32 v111, v111
	s_mov_b64 s[18:19], -1
	s_and_b64 vcc, exec, s[16:17]
	s_cbranch_vccnz .LBB0_295
	s_andn2_b64 vcc, exec, s[18:19]
	s_cbranch_vccz .LBB0_300
.LBB0_272:
	s_andn2_b64 vcc, exec, s[4:5]
	v_add_u32_e32 v225, s37, v255
	s_cbranch_vccnz .LBB0_274
.LBB0_273:
	s_waitcnt lgkmcnt(0)
	ds_read_b128 v[2:5], v225 offset:49248
	ds_read_b128 v[6:9], v225 offset:49216
	ds_read_b128 v[10:13], v225 offset:49184
	ds_read_b128 v[64:67], v225 offset:49152
	s_waitcnt lgkmcnt(3)
	v_pk_mul_f32 v[44:45], v[44:45], v[2:3]
	s_waitcnt lgkmcnt(2)
	v_pk_mul_f32 v[40:41], v[40:41], v[6:7]
	s_waitcnt lgkmcnt(1)
	v_pk_mul_f32 v[36:37], v[36:37], v[10:11]
	v_pk_mul_f32 v[46:47], v[46:47], v[4:5]
	v_pk_mul_f32 v[42:43], v[42:43], v[8:9]
	v_pk_mul_f32 v[38:39], v[38:39], v[12:13]
	s_waitcnt lgkmcnt(0)
	v_pk_mul_f32 v[34:35], v[34:35], v[66:67]
	v_pk_mul_f32 v[32:33], v[32:33], v[64:65]
	v_pk_mul_f32 v[28:29], v[28:29], v[2:3]
	v_pk_mul_f32 v[24:25], v[24:25], v[6:7]
	v_pk_mul_f32 v[20:21], v[20:21], v[10:11]
	v_pk_mul_f32 v[30:31], v[30:31], v[4:5]
	v_pk_mul_f32 v[26:27], v[26:27], v[8:9]
	v_pk_mul_f32 v[22:23], v[22:23], v[12:13]
	v_pk_mul_f32 v[18:19], v[18:19], v[66:67]
	v_pk_mul_f32 v[16:17], v[16:17], v[64:65]
	v_pk_mul_f32 v[238:239], v[238:239], v[2:3]
	v_pk_mul_f32 v[234:235], v[234:235], v[6:7]
	v_pk_mul_f32 v[230:231], v[230:231], v[10:11]
	v_pk_mul_f32 v[240:241], v[240:241], v[4:5]
	v_pk_mul_f32 v[236:237], v[236:237], v[8:9]
	v_pk_mul_f32 v[232:233], v[232:233], v[12:13]
	v_pk_mul_f32 v[228:229], v[228:229], v[66:67]
	v_pk_mul_f32 v[226:227], v[226:227], v[64:65]
	v_pk_mul_f32 v[220:221], v[220:221], v[2:3]
	v_pk_mul_f32 v[216:217], v[216:217], v[6:7]
	v_pk_mul_f32 v[212:213], v[212:213], v[10:11]
	v_pk_mul_f32 v[222:223], v[222:223], v[4:5]
	v_pk_mul_f32 v[218:219], v[218:219], v[8:9]
	v_pk_mul_f32 v[214:215], v[214:215], v[12:13]
	v_pk_mul_f32 v[210:211], v[210:211], v[66:67]
	v_pk_mul_f32 v[208:209], v[208:209], v[64:65]
.LBB0_274:
	v_add_u32_e32 v4, s41, v254
	s_add_i32 s45, s41, 0xe800
	ds_read_b64_tr_b16 v[200:201], v4 offset:24576
	ds_read_b64_tr_b16 v[202:203], v4 offset:25088
	s_waitcnt lgkmcnt(9)
	v_mfma_f32_32x32x16_bf16 v[80:95], v[188:191], v[148:151], v[48:63]
	v_add_f32_e32 v2, v112, v113
	v_add_f32_e32 v2, v114, v2
	v_add_f32_e32 v2, v115, v2
	v_add_f32_e32 v2, v116, v2
	v_add_f32_e32 v2, v117, v2
	v_cvt_pk_bf16_f32 v156, v112, v113
	v_cvt_pk_bf16_f32 v157, v114, v115
	ds_read_b64_tr_b16 v[196:197], v4 offset:28672
	ds_read_b64_tr_b16 v[198:199], v4 offset:29184
	s_waitcnt lgkmcnt(10)
	v_mfma_f32_32x32x16_bf16 v[64:79], v[184:187], v[148:151], v[48:63]
	v_add_f32_e32 v2, v118, v2
	v_add_f32_e32 v2, v119, v2
	v_add_f32_e32 v2, v120, v2
	v_add_f32_e32 v2, v121, v2
	v_cvt_pk_bf16_f32 v158, v116, v117
	v_cvt_pk_bf16_f32 v159, v118, v119
	ds_read_b64_tr_b16 v[192:193], v4 offset:25600
	ds_read_b64_tr_b16 v[194:195], v4 offset:26112
	s_waitcnt lgkmcnt(11)
	v_mfma_f32_32x32x16_bf16 v[80:95], v[180:183], v[140:143], v[80:95]
	v_add_f32_e32 v2, v122, v2
	v_add_f32_e32 v2, v123, v2
	v_add_f32_e32 v2, v124, v2
	v_add_f32_e32 v2, v125, v2
	v_cvt_pk_bf16_f32 v152, v120, v121
	v_cvt_pk_bf16_f32 v153, v122, v123
	ds_read_b64_tr_b16 v[116:117], v4 offset:29696
	ds_read_b64_tr_b16 v[118:119], v4 offset:30208
	s_waitcnt lgkmcnt(12)
	v_mfma_f32_32x32x16_bf16 v[64:79], v[176:179], v[140:143], v[64:79]
	v_add_f32_e32 v2, v126, v2
	v_add_f32_e32 v2, v127, v2
	v_add_f32_e32 v2, v96, v2
	v_add_f32_e32 v2, v97, v2
	v_cvt_pk_bf16_f32 v154, v124, v125
	v_cvt_pk_bf16_f32 v155, v126, v127
	ds_read_b64_tr_b16 v[112:113], v4 offset:26624
	ds_read_b64_tr_b16 v[114:115], v4 offset:27136
	s_waitcnt lgkmcnt(13)
	v_mfma_f32_32x32x16_bf16 v[80:95], v[172:175], v[132:135], v[80:95]
	v_add_f32_e32 v2, v98, v2
	v_add_f32_e32 v2, v99, v2
	v_add_f32_e32 v2, v100, v2
	v_add_f32_e32 v2, v101, v2
	v_cvt_pk_bf16_f32 v144, v96, v97
	v_cvt_pk_bf16_f32 v145, v98, v99
	ds_read_b64_tr_b16 v[10:11], v4 offset:30720
	ds_read_b64_tr_b16 v[12:13], v4 offset:31232
	s_waitcnt lgkmcnt(14)
	v_mfma_f32_32x32x16_bf16 v[64:79], v[168:171], v[132:135], v[64:79]
	v_add_f32_e32 v2, v102, v2
	v_add_f32_e32 v2, v103, v2
	v_add_f32_e32 v2, v104, v2
	v_add_f32_e32 v2, v105, v2
	v_cvt_pk_bf16_f32 v146, v100, v101
	v_cvt_pk_bf16_f32 v147, v102, v103
	ds_read_b64_tr_b16 v[6:7], v4 offset:27648
	ds_read_b64_tr_b16 v[8:9], v4 offset:28160
	s_waitcnt lgkmcnt(14)
	v_mfma_f32_32x32x16_bf16 v[80:95], v[164:167], v[128:131], v[80:95]
	v_add_f32_e32 v2, v106, v2
	v_add_f32_e32 v2, v107, v2
	v_add_f32_e32 v2, v108, v2
	v_add_f32_e32 v96, v109, v2
	v_cvt_pk_bf16_f32 v136, v104, v105
	v_cvt_pk_bf16_f32 v137, v106, v107
	ds_read_b64_tr_b16 v[2:3], v4 offset:31744
	ds_read_b64_tr_b16 v[4:5], v4 offset:32256
	v_mfma_f32_32x32x16_bf16 v[64:79], v[160:163], v[128:131], v[64:79]
	v_add_f32_e32 v96, v110, v96
	v_add_f32_e32 v96, v111, v96
	v_add_f32_e32 v96, 0, v96
	v_cvt_pk_bf16_f32 v138, v108, v109
	v_cvt_pk_bf16_f32 v139, v110, v111
	s_add_i32 s44, s21, 2
	s_cmp_ge_u32 s44, s40
	s_cselect_b64 s[18:19], -1, 0
	s_and_b64 vcc, exec, s[18:19]
	s_cbranch_vccnz .LBB0_276
	s_add_i32 s4, s42, s38
	s_mov_b32 s5, m0
	s_mov_b32 m0, s4
	s_nop 0
	global_load_lds_dwordx4 v[204:205], off
	s_mov_b32 m0, s5
.LBB0_276:
	s_add_i32 s4, s42, 0x2000
	s_cmpk_lg_i32 s42, 0x4000
	s_cselect_b32 s41, s4, 0
	s_cmp_lt_u32 s21, s40
	s_cselect_b64 s[22:23], -1, 0
	s_cmp_ge_u32 s21, s40
	s_cbranch_scc1 .LBB0_278
	v_lshl_add_u64 v[98:99], v[14:15], 0, s[96:97]
	s_add_i32 s4, s41, s39
	s_mov_b32 s5, m0
	s_mov_b32 m0, s4
	s_nop 0
	global_load_lds_dwordx4 v[98:99], off
	s_mov_b32 m0, s5
	s_add_i32 s46, s4, 0xe780
	s_mov_b32 s47, m0
	s_mov_b32 m0, s46
	s_nop 0
	global_load_lds_dwordx4 v[98:99], off offset:128
	s_mov_b32 m0, s47
; __device__ __forceinline__ void cmask(f32x16&p0,f32x16&p1,int jb,int qrel,int hi){
;   const float NEG=-INFINITY; int kb=64*jb+4*hi;
;   #pragma unroll
;   for(int r=0;r<16;++r){int kv=kb+(r&3)+8*(r>>2); if(kv>qrel)p0[r]=NEG; if(kv+32>qrel)p1[r]=NEG;}
; }
.LBB0_278:
	s_add_i32 s20, s20, -1
	s_cmp_lt_i32 s20, 0
	s_cbranch_scc1 .LBB0_280
	v_subrev_u32_e32 v98, 27, v0
	v_subrev_u32_e32 v97, 59, v0
	v_cmp_le_i32_e32 vcc, v98, v251
	s_nop 1
	v_cndmask_b32_e32 v64, v248, v64, vcc
	v_cmp_lt_i32_e32 vcc, v97, v251
	s_nop 1
	v_cndmask_b32_e32 v81, v248, v81, vcc
	v_cmp_le_i32_e32 vcc, v97, v251
	v_subrev_u32_e32 v97, 26, v0
	s_nop 0
	v_cndmask_b32_e32 v80, v248, v80, vcc
	v_cmp_le_i32_e32 vcc, v97, v251
	v_subrev_u32_e32 v97, 57, v0
	s_nop 0
	v_cndmask_b32_e32 v65, v248, v65, vcc
	v_cmp_le_i32_e32 vcc, v97, v251
	v_subrev_u32_e32 v97, 25, v0
	s_nop 0
	v_cndmask_b32_e32 v82, v248, v82, vcc
	v_cmp_le_i32_e32 vcc, v97, v251
	v_subrev_u32_e32 v97, 56, v0
	s_nop 0
	v_cndmask_b32_e32 v66, v248, v66, vcc
	v_cmp_le_i32_e32 vcc, v97, v251
	v_subrev_u32_e32 v97, 24, v0
	s_nop 0
	v_cndmask_b32_e32 v83, v248, v83, vcc
	v_cmp_le_i32_e32 vcc, v97, v251
	v_subrev_u32_e32 v97, 51, v0
	s_nop 0
	v_cndmask_b32_e32 v67, v248, v67, vcc
	v_cmp_le_i32_e32 vcc, v97, v251
	v_subrev_u32_e32 v97, 19, v0
	s_nop 0
	v_cndmask_b32_e32 v84, v248, v84, vcc
	v_cmp_le_i32_e32 vcc, v97, v251
	v_subrev_u32_e32 v97, 50, v0
	s_nop 0
	v_cndmask_b32_e32 v68, v248, v68, vcc
	v_cmp_le_i32_e32 vcc, v97, v251
	v_subrev_u32_e32 v97, 18, v0
	s_nop 0
	v_cndmask_b32_e32 v85, v248, v85, vcc
	v_cmp_le_i32_e32 vcc, v97, v251
	v_subrev_u32_e32 v97, 49, v0
	s_nop 0
	v_cndmask_b32_e32 v69, v248, v69, vcc
	v_cmp_le_i32_e32 vcc, v97, v251
	v_subrev_u32_e32 v97, 17, v0
	s_nop 0
	v_cndmask_b32_e32 v86, v248, v86, vcc
	v_cmp_le_i32_e32 vcc, v97, v251
	v_subrev_u32_e32 v97, 48, v0
	s_nop 0
	v_cndmask_b32_e32 v70, v248, v70, vcc
	v_cmp_le_i32_e32 vcc, v97, v251
	v_add_u32_e32 v97, -16, v0
	s_nop 0
	v_cndmask_b32_e32 v87, v248, v87, vcc
	v_cmp_le_i32_e32 vcc, v97, v251
	v_subrev_u32_e32 v97, 43, v0
	s_nop 0
	v_cndmask_b32_e32 v71, v248, v71, vcc
	v_cmp_le_i32_e32 vcc, v97, v251
	v_add_u32_e32 v97, -11, v0
	s_nop 0
	v_cndmask_b32_e32 v88, v248, v88, vcc
	v_cmp_le_i32_e32 vcc, v97, v251
	v_subrev_u32_e32 v97, 42, v0
	s_nop 0
	v_cndmask_b32_e32 v72, v248, v72, vcc
	v_cmp_le_i32_e32 vcc, v97, v251
	v_add_u32_e32 v97, -10, v0
	s_nop 0
	v_cndmask_b32_e32 v89, v248, v89, vcc
	v_cmp_le_i32_e32 vcc, v97, v251
	v_subrev_u32_e32 v97, 41, v0
	s_nop 0
	v_cndmask_b32_e32 v73, v248, v73, vcc
	v_cmp_le_i32_e32 vcc, v97, v251
	v_add_u32_e32 v97, -9, v0
	s_nop 0
	v_cndmask_b32_e32 v90, v248, v90, vcc
	v_cmp_le_i32_e32 vcc, v97, v251
	v_subrev_u32_e32 v97, 40, v0
	s_nop 0
	v_cndmask_b32_e32 v74, v248, v74, vcc
	v_cmp_le_i32_e32 vcc, v97, v251
	v_add_u32_e32 v97, -8, v0
	s_nop 0
	v_cndmask_b32_e32 v91, v248, v91, vcc
	v_cmp_le_i32_e32 vcc, v97, v251
	v_subrev_u32_e32 v97, 35, v0
	s_nop 0
	v_cndmask_b32_e32 v75, v248, v75, vcc
	v_cmp_le_i32_e32 vcc, v97, v251
	v_add_u32_e32 v97, -3, v0
	s_nop 0
	v_cndmask_b32_e32 v92, v248, v92, vcc
	v_cmp_le_i32_e32 vcc, v97, v251
	v_subrev_u32_e32 v97, 34, v0
	s_nop 0
	v_cndmask_b32_e32 v76, v248, v76, vcc
	v_cmp_le_i32_e32 vcc, v97, v251
	v_add_u32_e32 v97, -2, v0
	s_nop 0
	v_cndmask_b32_e32 v93, v248, v93, vcc
	v_cmp_le_i32_e32 vcc, v97, v251
	v_subrev_u32_e32 v97, 33, v0
	s_nop 0
	v_cndmask_b32_e32 v77, v248, v77, vcc
	v_cmp_le_i32_e32 vcc, v97, v251
	v_add_u32_e32 v97, -1, v0
	s_nop 0
	v_cndmask_b32_e32 v94, v248, v94, vcc
	v_cmp_le_i32_e32 vcc, v97, v251
	v_subrev_u32_e32 v97, 32, v0
	s_nop 0
	v_cndmask_b32_e32 v78, v248, v78, vcc
	v_cmp_le_i32_e32 vcc, v97, v251
	s_nop 1
	v_cndmask_b32_e32 v95, v248, v95, vcc
	v_cmp_le_i32_e32 vcc, v0, v251
	s_nop 1
	v_cndmask_b32_e32 v79, v248, v79, vcc

.LBB0_281:
	v_add_u32_e32 v96, s45, v254
	s_waitcnt lgkmcnt(14)
	v_mfma_f32_32x32x16_bf16 v[32:47], v[156:159], v[200:203], v[32:47]
	v_exp_f32_e32 v80, v80
	v_exp_f32_e32 v81, v81
	ds_read_b64_tr_b16 v[200:201], v96 offset:24576
	ds_read_b64_tr_b16 v[202:203], v96 offset:25088
	s_waitcnt lgkmcnt(14)
	v_mfma_f32_32x32x16_bf16 v[16:31], v[156:159], v[196:199], v[16:31]
	v_exp_f32_e32 v82, v82
	v_exp_f32_e32 v83, v83
	ds_read_b64_tr_b16 v[196:197], v96 offset:28672
	ds_read_b64_tr_b16 v[198:199], v96 offset:29184
	s_waitcnt lgkmcnt(14)
	v_mfma_f32_32x32x16_bf16 v[32:47], v[152:155], v[192:195], v[32:47]
	v_exp_f32_e32 v84, v84
	v_exp_f32_e32 v85, v85
	ds_read_b64_tr_b16 v[192:193], v96 offset:25600
	ds_read_b64_tr_b16 v[194:195], v96 offset:26112
	s_waitcnt lgkmcnt(14)
	v_mfma_f32_32x32x16_bf16 v[16:31], v[152:155], v[116:119], v[16:31]
	v_exp_f32_e32 v86, v86
	v_exp_f32_e32 v87, v87
	ds_read_b64_tr_b16 v[116:117], v96 offset:29696
	ds_read_b64_tr_b16 v[118:119], v96 offset:30208
	s_waitcnt lgkmcnt(14)
	v_mfma_f32_32x32x16_bf16 v[32:47], v[144:147], v[112:115], v[32:47]
	v_exp_f32_e32 v88, v88
	v_exp_f32_e32 v89, v89
	ds_read_b64_tr_b16 v[112:113], v96 offset:26624
	ds_read_b64_tr_b16 v[114:115], v96 offset:27136
	s_waitcnt lgkmcnt(14)
	v_mfma_f32_32x32x16_bf16 v[16:31], v[144:147], v[10:13], v[16:31]
	v_exp_f32_e32 v90, v90
	v_exp_f32_e32 v91, v91
	ds_read_b64_tr_b16 v[10:11], v96 offset:30720
	ds_read_b64_tr_b16 v[12:13], v96 offset:31232
	s_waitcnt lgkmcnt(14)
	v_mfma_f32_32x32x16_bf16 v[32:47], v[136:139], v[6:9], v[32:47]
	v_exp_f32_e32 v92, v92
	v_exp_f32_e32 v93, v93
	ds_read_b64_tr_b16 v[6:7], v96 offset:27648
	ds_read_b64_tr_b16 v[8:9], v96 offset:28160
	s_waitcnt lgkmcnt(14)
	v_mfma_f32_32x32x16_bf16 v[16:31], v[136:139], v[2:5], v[16:31]
	v_exp_f32_e32 v94, v94
	v_exp_f32_e32 v95, v95
	ds_read_b64_tr_b16 v[2:3], v96 offset:31744
	ds_read_b64_tr_b16 v[4:5], v96 offset:32256
	s_waitcnt lgkmcnt(14)
	v_mfma_f32_32x32x16_bf16 v[226:241], v[156:159], v[200:203], v[226:241]
	v_exp_f32_e32 v64, v64
	v_exp_f32_e32 v65, v65
	s_waitcnt lgkmcnt(12)
	v_mfma_f32_32x32x16_bf16 v[208:223], v[156:159], v[196:199], v[208:223]
	v_exp_f32_e32 v66, v66
	v_exp_f32_e32 v67, v67
	v_cndmask_b32_e64 v96, 0, 1, s[22:23]
	v_cmp_ne_u32_e64 s[4:5], 1, v96
	s_andn2_b64 vcc, exec, s[22:23]
	v_add_u32_e32 v96, s41, v253
	s_cbranch_vccnz .LBB0_283
	ds_read_b128 v[188:191], v96
	ds_read_b128 v[184:187], v96 offset:512
.LBB0_283:
	s_waitcnt lgkmcnt(10)
	v_mfma_f32_32x32x16_bf16 v[226:241], v[152:155], v[192:195], v[226:241]
	v_exp_f32_e32 v68, v68
	v_exp_f32_e32 v69, v69
	s_and_b64 vcc, exec, s[4:5]
	s_cbranch_vccnz .LBB0_285
	ds_read_b128 v[180:183], v96 offset:2048
	ds_read_b128 v[176:179], v96 offset:2560
.LBB0_285:
	s_waitcnt lgkmcnt(8)
	v_mfma_f32_32x32x16_bf16 v[208:223], v[152:155], v[116:119], v[208:223]
	v_exp_f32_e32 v70, v70
	v_exp_f32_e32 v71, v71
	s_and_b64 vcc, exec, s[4:5]
	s_cbranch_vccnz .LBB0_287
	ds_read_b128 v[172:175], v96 offset:4096
	ds_read_b128 v[168:171], v96 offset:4608
.LBB0_287:
	s_waitcnt lgkmcnt(6)
	v_mfma_f32_32x32x16_bf16 v[226:241], v[144:147], v[112:115], v[226:241]
	v_exp_f32_e32 v72, v72
	v_exp_f32_e32 v73, v73
	s_and_b64 vcc, exec, s[4:5]
	s_cbranch_vccnz .LBB0_289
	ds_read_b128 v[164:167], v96 offset:6144
	ds_read_b128 v[160:163], v96 offset:6656
.LBB0_289:
	s_waitcnt lgkmcnt(4)
	v_mfma_f32_32x32x16_bf16 v[208:223], v[144:147], v[10:13], v[208:223]
	v_exp_f32_e32 v74, v74
	v_exp_f32_e32 v75, v75
	s_waitcnt lgkmcnt(2)
	v_mfma_f32_32x32x16_bf16 v[226:241], v[136:139], v[6:9], v[226:241]
	v_exp_f32_e32 v76, v76
	v_exp_f32_e32 v77, v77
	s_waitcnt lgkmcnt(0)
	v_mfma_f32_32x32x16_bf16 v[208:223], v[136:139], v[2:5], v[208:223]
	v_exp_f32_e32 v78, v78
	v_exp_f32_e32 v79, v79
	s_mov_b64 s[4:5], -1
	s_and_b64 vcc, exec, s[18:19]
	s_cbranch_vccnz .LBB0_301
	s_andn2_b64 vcc, exec, s[4:5]
	s_cbranch_vccz .LBB0_306

;   #define RESC() do{ if(resc){ asm volatile("s_waitcnt lgkmcnt(0)":::"memory"); \
;       _Pragma("unroll") for(int d_=0;d_<2;++d_) _Pragma("unroll") for(int r=0;r<16;++r)o[d_][r]*=wsf[crow(r,hi)]; } }while(0)
;   #define ROT() do{sl_prev=sl_cur;sl_cur=sl_next;sl_next=(sl_next==(NSLOT-1)*SLOTB)?0:sl_next+SLOTB;}while(0)
;   #define ENDW(tt) do{ if((tt)+3<NT){WAIT_BAR(2);} else if((tt)+2<NT){WAIT_BAR(1);} else {WAIT_BAR(0);} }while(0)
; template<int THRL> __device__ __forceinline__ void attn_unit(int b,int colq,int colk,int colv,int colo,int qb,const bf16*Q,const bf16*__restrict__ K,const bf16*__restrict__ V,bf16*O,char*shm,const int tid_in){
;     ...
;   for(;t+1<NT;t+=2){
;     STEP(pB0,pB1,pA0,pA1,t,(t+3<NT),(t+1<NT),(t+1<NT));       ENDW(t);   RESC(); ROT();
;     STEP(pA0,pA1,pB0,pB1,t+1,(t+4<NT),(t+2<NT),(t+2<NT));     ENDW(t+1); RESC(); ROT();
;   }
.LBB0_292:
	s_waitcnt lgkmcnt(0)
	ds_read_b128 v[2:5], v225 offset:49248
	ds_read_b128 v[6:9], v225 offset:49216
	ds_read_b128 v[10:13], v225 offset:49184
	ds_read_b128 v[96:99], v225 offset:49152
	s_waitcnt lgkmcnt(3)
	v_pk_mul_f32 v[44:45], v[44:45], v[2:3]
	s_waitcnt lgkmcnt(2)
	v_pk_mul_f32 v[40:41], v[40:41], v[6:7]
	s_waitcnt lgkmcnt(1)
	v_pk_mul_f32 v[36:37], v[36:37], v[10:11]
	v_pk_mul_f32 v[46:47], v[46:47], v[4:5]
	v_pk_mul_f32 v[42:43], v[42:43], v[8:9]
	v_pk_mul_f32 v[38:39], v[38:39], v[12:13]
	s_waitcnt lgkmcnt(0)
	v_pk_mul_f32 v[34:35], v[34:35], v[98:99]
	v_pk_mul_f32 v[32:33], v[32:33], v[96:97]
	v_pk_mul_f32 v[28:29], v[28:29], v[2:3]
	v_pk_mul_f32 v[24:25], v[24:25], v[6:7]
	v_pk_mul_f32 v[20:21], v[20:21], v[10:11]
	v_pk_mul_f32 v[30:31], v[30:31], v[4:5]
	v_pk_mul_f32 v[26:27], v[26:27], v[8:9]
	v_pk_mul_f32 v[22:23], v[22:23], v[12:13]
	v_pk_mul_f32 v[18:19], v[18:19], v[98:99]
	v_pk_mul_f32 v[16:17], v[16:17], v[96:97]
	v_pk_mul_f32 v[238:239], v[238:239], v[2:3]
	v_pk_mul_f32 v[234:235], v[234:235], v[6:7]
	v_pk_mul_f32 v[230:231], v[230:231], v[10:11]
	v_pk_mul_f32 v[240:241], v[240:241], v[4:5]
	v_pk_mul_f32 v[236:237], v[236:237], v[8:9]
	v_pk_mul_f32 v[232:233], v[232:233], v[12:13]
	v_pk_mul_f32 v[228:229], v[228:229], v[98:99]
	v_pk_mul_f32 v[226:227], v[226:227], v[96:97]
	v_pk_mul_f32 v[220:221], v[220:221], v[2:3]
	v_pk_mul_f32 v[216:217], v[216:217], v[6:7]
	v_pk_mul_f32 v[212:213], v[212:213], v[10:11]
	v_pk_mul_f32 v[222:223], v[222:223], v[4:5]
	v_pk_mul_f32 v[218:219], v[218:219], v[8:9]
	v_pk_mul_f32 v[214:215], v[214:215], v[12:13]
	v_pk_mul_f32 v[210:211], v[210:211], v[98:99]
	v_pk_mul_f32 v[208:209], v[208:209], v[96:97]
.LBB0_293:
	s_add_i32 s4, s41, 0x2000
	s_cmpk_lg_i32 s41, 0x4000
	s_cselect_b32 s4, s4, 0
	s_add_i32 s5, s44, -1
	v_add_u32_e32 v0, 0x80, v0
	v_lshl_add_u64 v[14:15], v[14:15], 0, s[66:67]
	s_cmp_lt_u32 s5, s40
	v_lshl_add_u64 v[204:205], v[204:205], 0, s[66:67]
	s_cbranch_scc0 .LBB0_258
	s_mov_b32 s21, s44
	s_mov_b32 s20, s42
	s_mov_b32 s42, s4
	s_branch .LBB0_265

.LBB0_300:
	s_waitcnt vmcnt(2) lgkmcnt(0)
	s_barrier
	s_andn2_b64 vcc, exec, s[4:5]
	v_add_u32_e32 v225, s37, v255
	s_cbranch_vccz .LBB0_273
	s_branch .LBB0_274

.LBB0_307:
	v_max_f32_e32 v48, v76, v76
	v_max_f32_e32 v76, 0, v48
	v_exp_f32_e64 v77, -v76
	v_add_f32_e32 v252, v252, v76
	v_xor_b32_e32 v48, 0x80000000, v252
	v_mov_b32_e32 v49, v48
	v_mov_b32_e32 v50, v48
	v_mov_b32_e32 v51, v48
	v_mov_b32_e32 v52, v48
	v_mov_b32_e32 v53, v48
	v_mov_b32_e32 v54, v48
	v_mov_b32_e32 v55, v48
	v_mov_b32_e32 v56, v48
	v_mov_b32_e32 v57, v48
	v_mov_b32_e32 v58, v48
	v_mov_b32_e32 v59, v48
	v_mov_b32_e32 v60, v48
	v_mov_b32_e32 v61, v48
	v_mov_b32_e32 v62, v48
	v_mov_b32_e32 v63, v48
	s_and_saveexec_b64 s[18:19], s[2:3]
	ds_write_b32 v250, v77 offset:49152
	s_or_b64 exec, exec, s[18:19]
	v_sub_f32_e32 v127, v127, v76
	v_sub_f32_e32 v126, v126, v76
	v_sub_f32_e32 v125, v125, v76
	v_sub_f32_e32 v124, v124, v76
	v_sub_f32_e32 v123, v123, v76
	v_sub_f32_e32 v122, v122, v76
	v_sub_f32_e32 v121, v121, v76
	v_sub_f32_e32 v120, v120, v76
	v_sub_f32_e32 v119, v119, v76
	v_sub_f32_e32 v118, v118, v76
	v_sub_f32_e32 v117, v117, v76
	v_sub_f32_e32 v116, v116, v76
	v_sub_f32_e32 v115, v115, v76
	v_sub_f32_e32 v114, v114, v76
	v_sub_f32_e32 v113, v113, v76
	v_sub_f32_e32 v112, v112, v76
	v_sub_f32_e32 v111, v111, v76
	v_sub_f32_e32 v110, v110, v76
	v_sub_f32_e32 v109, v109, v76
	v_sub_f32_e32 v108, v108, v76
	v_sub_f32_e32 v107, v107, v76
	v_sub_f32_e32 v106, v106, v76
	v_sub_f32_e32 v105, v105, v76
	v_sub_f32_e32 v104, v104, v76
	v_sub_f32_e32 v103, v103, v76
	v_sub_f32_e32 v102, v102, v76
	v_sub_f32_e32 v101, v101, v76
	v_sub_f32_e32 v100, v100, v76
	v_sub_f32_e32 v99, v99, v76
	v_sub_f32_e32 v98, v98, v76
	v_sub_f32_e32 v97, v97, v76
	v_sub_f32_e32 v96, v96, v76
	v_mul_f32_e32 v224, v224, v77
	s_branch .LBB0_270
.LBB0_310:
	v_max_f32_e32 v48, v96, v96
	v_max_f32_e32 v96, 0, v48
	v_exp_f32_e64 v97, -v96
	v_add_f32_e32 v252, v252, v96
	v_xor_b32_e32 v48, 0x80000000, v252
	v_mov_b32_e32 v49, v48
	v_mov_b32_e32 v50, v48
	v_mov_b32_e32 v51, v48
	v_mov_b32_e32 v52, v48
	v_mov_b32_e32 v53, v48
	v_mov_b32_e32 v54, v48
	v_mov_b32_e32 v55, v48
	v_mov_b32_e32 v56, v48
	v_mov_b32_e32 v57, v48
	v_mov_b32_e32 v58, v48
	v_mov_b32_e32 v59, v48
	v_mov_b32_e32 v60, v48
	v_mov_b32_e32 v61, v48
	v_mov_b32_e32 v62, v48
	v_mov_b32_e32 v63, v48
	s_and_saveexec_b64 s[4:5], s[2:3]
	ds_write_b32 v250, v97 offset:49152
	s_or_b64 exec, exec, s[4:5]
	v_sub_f32_e32 v95, v95, v96
	v_sub_f32_e32 v94, v94, v96
	v_sub_f32_e32 v93, v93, v96
	v_sub_f32_e32 v92, v92, v96
	v_sub_f32_e32 v91, v91, v96
	v_sub_f32_e32 v90, v90, v96
	v_sub_f32_e32 v89, v89, v96
	v_sub_f32_e32 v88, v88, v96
	v_sub_f32_e32 v87, v87, v96
	v_sub_f32_e32 v86, v86, v96
	v_sub_f32_e32 v85, v85, v96
	v_sub_f32_e32 v84, v84, v96
	v_sub_f32_e32 v83, v83, v96
	v_sub_f32_e32 v82, v82, v96
	v_sub_f32_e32 v81, v81, v96
	v_sub_f32_e32 v80, v80, v96
	v_sub_f32_e32 v79, v79, v96
	v_sub_f32_e32 v78, v78, v96
	v_sub_f32_e32 v77, v77, v96
	v_sub_f32_e32 v76, v76, v96
	v_sub_f32_e32 v75, v75, v96
	v_sub_f32_e32 v74, v74, v96
	v_sub_f32_e32 v73, v73, v96
	v_sub_f32_e32 v72, v72, v96
	v_sub_f32_e32 v71, v71, v96
	v_sub_f32_e32 v70, v70, v96
	v_sub_f32_e32 v69, v69, v96
	v_sub_f32_e32 v68, v68, v96
	v_sub_f32_e32 v67, v67, v96
	v_sub_f32_e32 v66, v66, v96
	v_sub_f32_e32 v65, v65, v96
	v_sub_f32_e32 v64, v64, v96
	v_mul_f32_e32 v224, v224, v97
	s_branch .LBB0_281
.LBB0_313:
	v_max_f32_e32 v14, v14, v14
	v_max_f32_e32 v14, 0, v14
	v_add_f32_e32 v15, v252, v14
	v_xor_b32_e32 v80, 0x80000000, v15
	v_exp_f32_e64 v15, -v14
	v_mov_b32_e32 v81, v80
	v_mov_b32_e32 v82, v80
	v_mov_b32_e32 v83, v80
	v_mov_b32_e32 v84, v80
	v_mov_b32_e32 v85, v80
	v_mov_b32_e32 v86, v80
	v_mov_b32_e32 v87, v80
	v_mov_b32_e32 v88, v80
	v_mov_b32_e32 v89, v80
	v_mov_b32_e32 v90, v80
	v_mov_b32_e32 v91, v80
	v_mov_b32_e32 v92, v80
	v_mov_b32_e32 v93, v80
	v_mov_b32_e32 v94, v80
	v_mov_b32_e32 v95, v80
	v_cmp_gt_u32_e32 vcc, 32, v206
	s_and_saveexec_b64 s[4:5], vcc
	ds_write_b32 v250, v15 offset:49152
	s_or_b64 exec, exec, s[4:5]
	v_sub_f32_e32 v79, v79, v14
	v_sub_f32_e32 v78, v78, v14
	v_sub_f32_e32 v77, v77, v14
	v_sub_f32_e32 v76, v76, v14
	v_sub_f32_e32 v75, v75, v14
	v_sub_f32_e32 v74, v74, v14
	v_sub_f32_e32 v73, v73, v14
	v_sub_f32_e32 v72, v72, v14
	v_sub_f32_e32 v71, v71, v14
	v_sub_f32_e32 v70, v70, v14
	v_sub_f32_e32 v69, v69, v14
	v_sub_f32_e32 v68, v68, v14
	v_sub_f32_e32 v67, v67, v14
	v_sub_f32_e32 v66, v66, v14
	v_sub_f32_e32 v65, v65, v14
	v_sub_f32_e32 v64, v64, v14
	v_sub_f32_e32 v63, v63, v14
	v_sub_f32_e32 v62, v62, v14
	v_sub_f32_e32 v61, v61, v14
	v_sub_f32_e32 v60, v60, v14
	v_sub_f32_e32 v59, v59, v14
	v_sub_f32_e32 v58, v58, v14
	v_sub_f32_e32 v57, v57, v14
	v_sub_f32_e32 v56, v56, v14
	v_sub_f32_e32 v55, v55, v14
	v_sub_f32_e32 v54, v54, v14
	v_sub_f32_e32 v53, v53, v14
	v_sub_f32_e32 v52, v52, v14
	v_sub_f32_e32 v51, v51, v14
	v_sub_f32_e32 v50, v50, v14
	v_sub_f32_e32 v49, v49, v14
	v_sub_f32_e32 v48, v48, v14
	v_mul_f32_e32 v0, v0, v15
	s_branch .LBB0_259

; #define PHASE_IDS() int tid = tid0; asm volatile("" : "+v"(tid)); const int lane = tid & 63, wave = __builtin_amdgcn_readfirstlane(tid >> 6), gw = bx * 8 + wave; (void)lane; (void)gw;
; __device__ __forceinline__ void diff_combine_block(const u16* AUX, u16* MIX, const float* lam_p, const float* subg, size_t row0, int h, int tid) {
;     const int lane = tid & 63;
;     const float s01 = wave_sum(lam_p[lane] * lam_p[64 + lane], lane), s23 = wave_sum(lam_p[128 + lane] * lam_p[192 + lane], lane);
;     const float lam = __expf(s01) - __expf(s23) + 0.2f;
;     const int d0 = (tid & 15) * 8;
;     float gv[8];
; #pragma unroll
;     for (int e = 0; e < 8; ++e) gv[e] = subg[d0 + e] * 0.8f;
; __global__ void __launch_bounds__(512, 2) fwd_kernel(Args A) {
;     ...
;                     asm volatile("s_waitcnt vmcnt(0)" ::: "memory");
;                     __syncthreads();
;                     for (int grp = 0; grp < 2; ++grp) { PHASE_IDS(); diff_combine_block(AUX, MIX, A.da_lambda, A.da_subln_g, (size_t)b * 8192 + (size_t)(grp ? jq : 31 - jq) * 256, hh, tid); }
.LBB0_397:
	v_mbcnt_lo_u32_b32 v0, -1, 0
	v_mbcnt_hi_u32_b32 v0, -1, v0
	v_add_u32_e32 v0, s33, v0
	v_lshlrev_b32_e32 v0, 2, v0
	v_add_u32_e32 v0, 0x1a800, v0
	ds_read_b32 v226, v0
	ds_read_b32 v244, v0 offset:2048
	ds_read_b32 v245, v0 offset:4096
	ds_read_b32 v247, v0 offset:6144
	ds_read_b32 v250, v0 offset:8192
	ds_read_b32 v253, v0 offset:10240
	ds_read_b32 v254, v0 offset:12288
	ds_read_b32 v255, v0 offset:14336
	s_waitcnt lgkmcnt(0)
	s_lshl_b32 s2, s26, 9
	v_readlane_b32 s0, v253, 57
	s_add_u32 s4, s0, s2
	v_readlane_b32 s0, v253, 58
	s_addc_u32 s5, s0, 0
	s_lshl_b32 s2, s24, 1
	v_readlane_b32 s12, v253, 37
	s_waitcnt vmcnt(0)
	v_readlane_b32 s13, v253, 38
	v_readlane_b32 s14, v253, 39
	v_readlane_b32 s15, v253, 40
	v_readlane_b32 s20, v253, 45
	v_readlane_b32 s21, v253, 46
	s_add_u32 s8, s82, s2
	v_readlane_b32 s16, v253, 41
	v_readlane_b32 s17, v253, 42
	v_readlane_b32 s18, v253, 43
	v_readlane_b32 s19, v253, 44
	v_readlane_b32 s22, v253, 47
	v_readlane_b32 s23, v253, 48
	v_readlane_b32 s24, v253, 49
	v_readlane_b32 s25, v253, 50
	v_readlane_b32 s26, v253, 51
	v_readlane_b32 s27, v253, 52
	s_mov_b64 s[12:13], s[20:21]
	s_addc_u32 s9, s83, 0
	s_mov_b64 s[10:11], -1
	s_mov_b64 s[14:15], s[22:23]
	v_readlane_b32 s0, v255, 18
	v_readlane_b32 s1, v255, 19
	s_movk_i32 s16, 0x80
	s_mov_b32 s17, 0x10000
	s_mov_b32 s18, 0x40000
	s_mov_b32 s19, 0x70000
	s_mov_b32 s20, 0x20000
	s_mov_b32 s21, 0x30000
	s_mov_b32 s22, 0x50000
	s_mov_b32 s23, 0x60000
	s_mov_b64 s[24:25], 0x10000
	s_mov_b64 s[26:27], 0x40000
	s_mov_b64 s[28:29], 0x20000
	s_mov_b32 s30, 0x3f4ccccd
	s_mov_b64 s[34:35], 0x30000
	s_mov_b64 s[36:37], 0x50000
	s_mov_b64 s[38:39], 0x60000
	s_barrier
